# K-loops of up-proj and in-proj GEMM phases rewritten by hand: ds_write/global_load interleaved between MFMAs (fine-grained), 2 register stages
# speedup vs baseline: 1.0476x; 1.0476x over previous
.LBB0_20:
	s_mov_b32 s18, 0x10000
	s_mov_b32 s19, 0
	v_lshl_add_u64 v[138:139], s[18:19], 0, v[132:133]
	s_mov_b32 s18, 0x20000
	s_mov_b32 s19, 0
	v_lshl_add_u64 v[172:173], s[18:19], 0, v[132:133]
	s_mov_b32 s18, 0x30000
	s_mov_b32 s19, 0
	v_lshl_add_u64 v[174:175], s[18:19], 0, v[132:133]
	s_mov_b32 s18, 0x10000
	s_mov_b32 s19, 0
	v_lshl_add_u64 v[176:177], s[18:19], 0, v[134:135]
	s_mov_b32 s18, 0x580000
	s_mov_b32 s19, 0
	v_lshl_add_u64 v[178:179], s[18:19], 0, v[134:135]
	s_mov_b32 s18, 0x590000
	s_mov_b32 s19, 0
	v_lshl_add_u64 v[180:181], s[18:19], 0, v[134:135]
	v_lshrrev_b32_e32 v186, 3, v0
	v_lshlrev_b32_e32 v187, 4, v0
	v_mul_u32_u24_e32 v186, 0x90, v186
	v_and_b32_e32 v187, 0x70, v187
	v_add_u32_e32 v182, v186, v187
	v_add_u32_e32 v183, 0x9000, v182
	v_lshrrev_b32_e32 v186, 1, v0
	v_and_b32_e32 v187, 31, v0
	v_and_b32_e32 v194, 16, v186
	v_and_b32_e32 v186, 64, v186
	v_add_u32_e32 v186, v186, v187
	v_mul_u32_u24_e32 v186, 0x90, v186
	v_add_u32_e32 v184, v186, v194
	v_and_b32_e32 v186, 64, v0
	v_add_u32_e32 v186, v186, v187
	v_mul_u32_u24_e32 v186, 0x90, v186
	v_add_u32_e32 v185, v186, v194
	s_barrier
	s_waitcnt vmcnt(15)
	ds_write_b128 v182, v[68:71]
	s_waitcnt vmcnt(13)
	ds_write_b128 v182, v[72:75] offset:4608
	s_waitcnt vmcnt(11)
	ds_write_b128 v182, v[76:79] offset:9216
	s_waitcnt vmcnt(9)
	ds_write_b128 v182, v[80:83] offset:13824
	s_waitcnt vmcnt(7)
	ds_write_b128 v182, v[84:87] offset:18432
	s_waitcnt vmcnt(5)
	ds_write_b128 v182, v[88:91] offset:23040
	s_waitcnt vmcnt(3)
	ds_write_b128 v182, v[92:95] offset:27648
	s_waitcnt vmcnt(1)
	ds_write_b128 v182, v[96:99] offset:32256
	global_load_dwordx4 v[68:71], v[132:133], off offset:256
	global_load_dwordx4 v[72:75], v[138:139], off offset:256
	global_load_dwordx4 v[76:79], v[172:173], off offset:256
	global_load_dwordx4 v[80:83], v[174:175], off offset:256
	global_load_dwordx4 v[84:87], v[134:135], off offset:256
	global_load_dwordx4 v[88:91], v[176:177], off offset:256
	global_load_dwordx4 v[92:95], v[178:179], off offset:256
	global_load_dwordx4 v[96:99], v[180:181], off offset:256
	s_waitcnt lgkmcnt(0)
	s_barrier
	ds_read_b128 v[140:143], v184
	ds_read_b128 v[144:147], v185 offset:18432
	ds_read_b128 v[148:151], v185 offset:23040
	ds_read_b128 v[152:155], v184 offset:4608
	ds_read_b128 v[156:159], v184 offset:32
	ds_read_b128 v[160:163], v185 offset:18464
	ds_read_b128 v[164:167], v185 offset:23072
	ds_read_b128 v[168:171], v184 offset:4640
	s_setprio 1
	s_waitcnt lgkmcnt(6)
	v_mfma_f32_32x32x16_bf16 v[52:67], v[144:147], v[140:143], 0
	ds_write_b128 v183, v[100:103]
	s_waitcnt lgkmcnt(6)
	v_mfma_f32_32x32x16_bf16 v[36:51], v[148:151], v[140:143], 0
	ds_write_b128 v183, v[104:107] offset:4608
	s_waitcnt lgkmcnt(6)
	v_mfma_f32_32x32x16_bf16 v[20:35], v[144:147], v[152:155], 0
	ds_write_b128 v183, v[108:111] offset:9216
	global_load_dwordx4 v[100:103], v[132:133], off offset:384
	v_mfma_f32_32x32x16_bf16 v[4:19], v[148:151], v[152:155], 0
	ds_read_b128 v[140:143], v184 offset:64
	ds_read_b128 v[144:147], v185 offset:18496
	s_waitcnt lgkmcnt(7)
	v_mfma_f32_32x32x16_bf16 v[52:67], v[160:163], v[156:159], v[52:67]
	ds_read_b128 v[148:151], v185 offset:23104
	ds_read_b128 v[152:155], v184 offset:4672
	s_waitcnt lgkmcnt(8)
	v_mfma_f32_32x32x16_bf16 v[36:51], v[164:167], v[156:159], v[36:51]
	ds_write_b128 v183, v[112:115] offset:13824
	global_load_dwordx4 v[104:107], v[138:139], off offset:384
	s_waitcnt lgkmcnt(8)
	v_mfma_f32_32x32x16_bf16 v[20:35], v[160:163], v[168:171], v[20:35]
	ds_write_b128 v183, v[116:119] offset:18432
	global_load_dwordx4 v[108:111], v[172:173], off offset:384
	v_mfma_f32_32x32x16_bf16 v[4:19], v[164:167], v[168:171], v[4:19]
	ds_read_b128 v[156:159], v184 offset:96
	ds_read_b128 v[160:163], v185 offset:18528
	s_waitcnt lgkmcnt(6)
	v_mfma_f32_32x32x16_bf16 v[52:67], v[144:147], v[140:143], v[52:67]
	ds_read_b128 v[164:167], v185 offset:23136
	ds_read_b128 v[168:171], v184 offset:4704
	s_waitcnt lgkmcnt(7)
	v_mfma_f32_32x32x16_bf16 v[36:51], v[148:151], v[140:143], v[36:51]
	ds_write_b128 v183, v[120:123] offset:23040
	global_load_dwordx4 v[112:115], v[174:175], off offset:384
	s_waitcnt lgkmcnt(7)
	v_mfma_f32_32x32x16_bf16 v[20:35], v[144:147], v[152:155], v[20:35]
	ds_write_b128 v183, v[124:127] offset:27648
	global_load_dwordx4 v[116:119], v[134:135], off offset:384
	v_mfma_f32_32x32x16_bf16 v[4:19], v[148:151], v[152:155], v[4:19]
	s_waitcnt vmcnt(13)
	ds_write_b128 v183, v[128:131] offset:32256
	global_load_dwordx4 v[120:123], v[176:177], off offset:384
	s_waitcnt lgkmcnt(5)
	v_mfma_f32_32x32x16_bf16 v[52:67], v[160:163], v[156:159], v[52:67]
	global_load_dwordx4 v[124:127], v[178:179], off offset:384
	s_waitcnt lgkmcnt(4)
	v_mfma_f32_32x32x16_bf16 v[36:51], v[164:167], v[156:159], v[36:51]
	global_load_dwordx4 v[128:131], v[180:181], off offset:384
	s_waitcnt lgkmcnt(3)
	v_mfma_f32_32x32x16_bf16 v[20:35], v[160:163], v[168:171], v[20:35]
	v_mfma_f32_32x32x16_bf16 v[4:19], v[164:167], v[168:171], v[4:19]
	s_setprio 0
	s_waitcnt lgkmcnt(0)
	s_barrier
	ds_read_b128 v[140:143], v184 offset:36864
	ds_read_b128 v[144:147], v185 offset:55296
	ds_read_b128 v[148:151], v185 offset:59904
	ds_read_b128 v[152:155], v184 offset:41472
	ds_read_b128 v[156:159], v184 offset:36896
	ds_read_b128 v[160:163], v185 offset:55328
	ds_read_b128 v[164:167], v185 offset:59936
	ds_read_b128 v[168:171], v184 offset:41504
	s_setprio 1
	s_waitcnt lgkmcnt(6)
	v_mfma_f32_32x32x16_bf16 v[52:67], v[144:147], v[140:143], v[52:67]
	s_waitcnt vmcnt(15)
	ds_write_b128 v182, v[68:71]
	s_waitcnt lgkmcnt(6)
	v_mfma_f32_32x32x16_bf16 v[36:51], v[148:151], v[140:143], v[36:51]
	s_waitcnt vmcnt(14)
	ds_write_b128 v182, v[72:75] offset:4608
	s_waitcnt lgkmcnt(6)
	v_mfma_f32_32x32x16_bf16 v[20:35], v[144:147], v[152:155], v[20:35]
	s_waitcnt vmcnt(13)
	ds_write_b128 v182, v[76:79] offset:9216
	global_load_dwordx4 v[68:71], v[132:133], off offset:512
	v_mfma_f32_32x32x16_bf16 v[4:19], v[148:151], v[152:155], v[4:19]
	ds_read_b128 v[140:143], v184 offset:36928
	ds_read_b128 v[144:147], v185 offset:55360
	s_waitcnt lgkmcnt(7)
	v_mfma_f32_32x32x16_bf16 v[52:67], v[160:163], v[156:159], v[52:67]
	ds_read_b128 v[148:151], v185 offset:59968
	ds_read_b128 v[152:155], v184 offset:41536
	s_waitcnt lgkmcnt(8)
	v_mfma_f32_32x32x16_bf16 v[36:51], v[164:167], v[156:159], v[36:51]
	s_waitcnt vmcnt(13)
	ds_write_b128 v182, v[80:83] offset:13824
	global_load_dwordx4 v[72:75], v[138:139], off offset:512
	s_waitcnt lgkmcnt(8)
	v_mfma_f32_32x32x16_bf16 v[20:35], v[160:163], v[168:171], v[20:35]
	s_waitcnt vmcnt(13)
	ds_write_b128 v182, v[84:87] offset:18432
	global_load_dwordx4 v[76:79], v[172:173], off offset:512
	v_mfma_f32_32x32x16_bf16 v[4:19], v[164:167], v[168:171], v[4:19]
	ds_read_b128 v[156:159], v184 offset:36960
	ds_read_b128 v[160:163], v185 offset:55392
	s_waitcnt lgkmcnt(6)
	v_mfma_f32_32x32x16_bf16 v[52:67], v[144:147], v[140:143], v[52:67]
	ds_read_b128 v[164:167], v185 offset:60000
	ds_read_b128 v[168:171], v184 offset:41568
	s_waitcnt lgkmcnt(7)
	v_mfma_f32_32x32x16_bf16 v[36:51], v[148:151], v[140:143], v[36:51]
	s_waitcnt vmcnt(13)
	ds_write_b128 v182, v[88:91] offset:23040
	global_load_dwordx4 v[80:83], v[174:175], off offset:512
	s_waitcnt lgkmcnt(7)
	v_mfma_f32_32x32x16_bf16 v[20:35], v[144:147], v[152:155], v[20:35]
	s_waitcnt vmcnt(13)
	ds_write_b128 v182, v[92:95] offset:27648
	global_load_dwordx4 v[84:87], v[134:135], off offset:512
	v_mfma_f32_32x32x16_bf16 v[4:19], v[148:151], v[152:155], v[4:19]
	s_waitcnt vmcnt(13)
	ds_write_b128 v182, v[96:99] offset:32256
	global_load_dwordx4 v[88:91], v[176:177], off offset:512
	s_waitcnt lgkmcnt(5)
	v_mfma_f32_32x32x16_bf16 v[52:67], v[160:163], v[156:159], v[52:67]
	global_load_dwordx4 v[92:95], v[178:179], off offset:512
	s_waitcnt lgkmcnt(4)
	v_mfma_f32_32x32x16_bf16 v[36:51], v[164:167], v[156:159], v[36:51]
	global_load_dwordx4 v[96:99], v[180:181], off offset:512
	s_waitcnt lgkmcnt(3)
	v_mfma_f32_32x32x16_bf16 v[20:35], v[160:163], v[168:171], v[20:35]
	v_mfma_f32_32x32x16_bf16 v[4:19], v[164:167], v[168:171], v[4:19]
	s_setprio 0
	s_waitcnt lgkmcnt(0)
	s_barrier
	ds_read_b128 v[140:143], v184
	ds_read_b128 v[144:147], v185 offset:18432
	ds_read_b128 v[148:151], v185 offset:23040
	ds_read_b128 v[152:155], v184 offset:4608
	ds_read_b128 v[156:159], v184 offset:32
	ds_read_b128 v[160:163], v185 offset:18464
	ds_read_b128 v[164:167], v185 offset:23072
	ds_read_b128 v[168:171], v184 offset:4640
	s_setprio 1
	s_waitcnt lgkmcnt(6)
	v_mfma_f32_32x32x16_bf16 v[52:67], v[144:147], v[140:143], v[52:67]
	s_waitcnt vmcnt(15)
	ds_write_b128 v183, v[100:103]
	s_waitcnt lgkmcnt(6)
	v_mfma_f32_32x32x16_bf16 v[36:51], v[148:151], v[140:143], v[36:51]
	s_waitcnt vmcnt(14)
	ds_write_b128 v183, v[104:107] offset:4608
	s_waitcnt lgkmcnt(6)
	v_mfma_f32_32x32x16_bf16 v[20:35], v[144:147], v[152:155], v[20:35]
	s_waitcnt vmcnt(13)
	ds_write_b128 v183, v[108:111] offset:9216
	global_load_dwordx4 v[100:103], v[132:133], off offset:640
	v_mfma_f32_32x32x16_bf16 v[4:19], v[148:151], v[152:155], v[4:19]
	ds_read_b128 v[140:143], v184 offset:64
	ds_read_b128 v[144:147], v185 offset:18496
	s_waitcnt lgkmcnt(7)
	v_mfma_f32_32x32x16_bf16 v[52:67], v[160:163], v[156:159], v[52:67]
	ds_read_b128 v[148:151], v185 offset:23104
	ds_read_b128 v[152:155], v184 offset:4672
	s_waitcnt lgkmcnt(8)
	v_mfma_f32_32x32x16_bf16 v[36:51], v[164:167], v[156:159], v[36:51]
	s_waitcnt vmcnt(13)
	ds_write_b128 v183, v[112:115] offset:13824
	global_load_dwordx4 v[104:107], v[138:139], off offset:640
	s_waitcnt lgkmcnt(8)
	v_mfma_f32_32x32x16_bf16 v[20:35], v[160:163], v[168:171], v[20:35]
	s_waitcnt vmcnt(13)
	ds_write_b128 v183, v[116:119] offset:18432
	global_load_dwordx4 v[108:111], v[172:173], off offset:640
	v_mfma_f32_32x32x16_bf16 v[4:19], v[164:167], v[168:171], v[4:19]
	ds_read_b128 v[156:159], v184 offset:96
	ds_read_b128 v[160:163], v185 offset:18528
	s_waitcnt lgkmcnt(6)
	v_mfma_f32_32x32x16_bf16 v[52:67], v[144:147], v[140:143], v[52:67]
	ds_read_b128 v[164:167], v185 offset:23136
	ds_read_b128 v[168:171], v184 offset:4704
	s_waitcnt lgkmcnt(7)
	v_mfma_f32_32x32x16_bf16 v[36:51], v[148:151], v[140:143], v[36:51]
	s_waitcnt vmcnt(13)
	ds_write_b128 v183, v[120:123] offset:23040
	global_load_dwordx4 v[112:115], v[174:175], off offset:640
	s_waitcnt lgkmcnt(7)
	v_mfma_f32_32x32x16_bf16 v[20:35], v[144:147], v[152:155], v[20:35]
	s_waitcnt vmcnt(13)
	ds_write_b128 v183, v[124:127] offset:27648
	global_load_dwordx4 v[116:119], v[134:135], off offset:640
	v_mfma_f32_32x32x16_bf16 v[4:19], v[148:151], v[152:155], v[4:19]
	s_waitcnt vmcnt(13)
	ds_write_b128 v183, v[128:131] offset:32256
	global_load_dwordx4 v[120:123], v[176:177], off offset:640
	s_waitcnt lgkmcnt(5)
	v_mfma_f32_32x32x16_bf16 v[52:67], v[160:163], v[156:159], v[52:67]
	global_load_dwordx4 v[124:127], v[178:179], off offset:640
	s_waitcnt lgkmcnt(4)
	v_mfma_f32_32x32x16_bf16 v[36:51], v[164:167], v[156:159], v[36:51]
	global_load_dwordx4 v[128:131], v[180:181], off offset:640
	s_waitcnt lgkmcnt(3)
	v_mfma_f32_32x32x16_bf16 v[20:35], v[160:163], v[168:171], v[20:35]
	v_mfma_f32_32x32x16_bf16 v[4:19], v[164:167], v[168:171], v[4:19]
	s_setprio 0
	s_waitcnt lgkmcnt(0)
	s_barrier
	ds_read_b128 v[140:143], v184 offset:36864
	ds_read_b128 v[144:147], v185 offset:55296
	ds_read_b128 v[148:151], v185 offset:59904
	ds_read_b128 v[152:155], v184 offset:41472
	ds_read_b128 v[156:159], v184 offset:36896
	ds_read_b128 v[160:163], v185 offset:55328
	ds_read_b128 v[164:167], v185 offset:59936
	ds_read_b128 v[168:171], v184 offset:41504
	s_setprio 1
	s_waitcnt lgkmcnt(6)
	v_mfma_f32_32x32x16_bf16 v[52:67], v[144:147], v[140:143], v[52:67]
	s_waitcnt vmcnt(15)
	ds_write_b128 v182, v[68:71]
	s_waitcnt lgkmcnt(6)
	v_mfma_f32_32x32x16_bf16 v[36:51], v[148:151], v[140:143], v[36:51]
	s_waitcnt vmcnt(14)
	ds_write_b128 v182, v[72:75] offset:4608
	s_waitcnt lgkmcnt(6)
	v_mfma_f32_32x32x16_bf16 v[20:35], v[144:147], v[152:155], v[20:35]
	s_waitcnt vmcnt(13)
	ds_write_b128 v182, v[76:79] offset:9216
	global_load_dwordx4 v[68:71], v[132:133], off offset:768
	v_mfma_f32_32x32x16_bf16 v[4:19], v[148:151], v[152:155], v[4:19]
	ds_read_b128 v[140:143], v184 offset:36928
	ds_read_b128 v[144:147], v185 offset:55360
	s_waitcnt lgkmcnt(7)
	v_mfma_f32_32x32x16_bf16 v[52:67], v[160:163], v[156:159], v[52:67]
	ds_read_b128 v[148:151], v185 offset:59968
	ds_read_b128 v[152:155], v184 offset:41536
	s_waitcnt lgkmcnt(8)
	v_mfma_f32_32x32x16_bf16 v[36:51], v[164:167], v[156:159], v[36:51]
	s_waitcnt vmcnt(13)
	ds_write_b128 v182, v[80:83] offset:13824
	global_load_dwordx4 v[72:75], v[138:139], off offset:768
	s_waitcnt lgkmcnt(8)
	v_mfma_f32_32x32x16_bf16 v[20:35], v[160:163], v[168:171], v[20:35]
	s_waitcnt vmcnt(13)
	ds_write_b128 v182, v[84:87] offset:18432
	global_load_dwordx4 v[76:79], v[172:173], off offset:768
	v_mfma_f32_32x32x16_bf16 v[4:19], v[164:167], v[168:171], v[4:19]
	ds_read_b128 v[156:159], v184 offset:36960
	ds_read_b128 v[160:163], v185 offset:55392
	s_waitcnt lgkmcnt(6)
	v_mfma_f32_32x32x16_bf16 v[52:67], v[144:147], v[140:143], v[52:67]
	ds_read_b128 v[164:167], v185 offset:60000
	ds_read_b128 v[168:171], v184 offset:41568
	s_waitcnt lgkmcnt(7)
	v_mfma_f32_32x32x16_bf16 v[36:51], v[148:151], v[140:143], v[36:51]
	s_waitcnt vmcnt(13)
	ds_write_b128 v182, v[88:91] offset:23040
	global_load_dwordx4 v[80:83], v[174:175], off offset:768
	s_waitcnt lgkmcnt(7)
	v_mfma_f32_32x32x16_bf16 v[20:35], v[144:147], v[152:155], v[20:35]
	s_waitcnt vmcnt(13)
	ds_write_b128 v182, v[92:95] offset:27648
	global_load_dwordx4 v[84:87], v[134:135], off offset:768
	v_mfma_f32_32x32x16_bf16 v[4:19], v[148:151], v[152:155], v[4:19]
	s_waitcnt vmcnt(13)
	ds_write_b128 v182, v[96:99] offset:32256
	global_load_dwordx4 v[88:91], v[176:177], off offset:768
	s_waitcnt lgkmcnt(5)
	v_mfma_f32_32x32x16_bf16 v[52:67], v[160:163], v[156:159], v[52:67]
	global_load_dwordx4 v[92:95], v[178:179], off offset:768
	s_waitcnt lgkmcnt(4)
	v_mfma_f32_32x32x16_bf16 v[36:51], v[164:167], v[156:159], v[36:51]
	global_load_dwordx4 v[96:99], v[180:181], off offset:768
	s_waitcnt lgkmcnt(3)
	v_mfma_f32_32x32x16_bf16 v[20:35], v[160:163], v[168:171], v[20:35]
	v_mfma_f32_32x32x16_bf16 v[4:19], v[164:167], v[168:171], v[4:19]
	s_setprio 0
	s_waitcnt lgkmcnt(0)
	s_barrier
	ds_read_b128 v[140:143], v184
	ds_read_b128 v[144:147], v185 offset:18432
	ds_read_b128 v[148:151], v185 offset:23040
	ds_read_b128 v[152:155], v184 offset:4608
	ds_read_b128 v[156:159], v184 offset:32
	ds_read_b128 v[160:163], v185 offset:18464
	ds_read_b128 v[164:167], v185 offset:23072
	ds_read_b128 v[168:171], v184 offset:4640
	s_setprio 1
	s_waitcnt lgkmcnt(6)
	v_mfma_f32_32x32x16_bf16 v[52:67], v[144:147], v[140:143], v[52:67]
	s_waitcnt vmcnt(15)
	ds_write_b128 v183, v[100:103]
	s_waitcnt lgkmcnt(6)
	v_mfma_f32_32x32x16_bf16 v[36:51], v[148:151], v[140:143], v[36:51]
	s_waitcnt vmcnt(14)
	ds_write_b128 v183, v[104:107] offset:4608
	s_waitcnt lgkmcnt(6)
	v_mfma_f32_32x32x16_bf16 v[20:35], v[144:147], v[152:155], v[20:35]
	s_waitcnt vmcnt(13)
	ds_write_b128 v183, v[108:111] offset:9216
	global_load_dwordx4 v[100:103], v[132:133], off offset:896
	v_mfma_f32_32x32x16_bf16 v[4:19], v[148:151], v[152:155], v[4:19]
	ds_read_b128 v[140:143], v184 offset:64
	ds_read_b128 v[144:147], v185 offset:18496
	s_waitcnt lgkmcnt(7)
	v_mfma_f32_32x32x16_bf16 v[52:67], v[160:163], v[156:159], v[52:67]
	ds_read_b128 v[148:151], v185 offset:23104
	ds_read_b128 v[152:155], v184 offset:4672
	s_waitcnt lgkmcnt(8)
	v_mfma_f32_32x32x16_bf16 v[36:51], v[164:167], v[156:159], v[36:51]
	s_waitcnt vmcnt(13)
	ds_write_b128 v183, v[112:115] offset:13824
	global_load_dwordx4 v[104:107], v[138:139], off offset:896
	s_waitcnt lgkmcnt(8)
	v_mfma_f32_32x32x16_bf16 v[20:35], v[160:163], v[168:171], v[20:35]
	s_waitcnt vmcnt(13)
	ds_write_b128 v183, v[116:119] offset:18432
	global_load_dwordx4 v[108:111], v[172:173], off offset:896
	v_mfma_f32_32x32x16_bf16 v[4:19], v[164:167], v[168:171], v[4:19]
	ds_read_b128 v[156:159], v184 offset:96
	ds_read_b128 v[160:163], v185 offset:18528
	s_waitcnt lgkmcnt(6)
	v_mfma_f32_32x32x16_bf16 v[52:67], v[144:147], v[140:143], v[52:67]
	ds_read_b128 v[164:167], v185 offset:23136
	ds_read_b128 v[168:171], v184 offset:4704
	s_waitcnt lgkmcnt(7)
	v_mfma_f32_32x32x16_bf16 v[36:51], v[148:151], v[140:143], v[36:51]
	s_waitcnt vmcnt(13)
	ds_write_b128 v183, v[120:123] offset:23040
	global_load_dwordx4 v[112:115], v[174:175], off offset:896
	s_waitcnt lgkmcnt(7)
	v_mfma_f32_32x32x16_bf16 v[20:35], v[144:147], v[152:155], v[20:35]
	s_waitcnt vmcnt(13)
	ds_write_b128 v183, v[124:127] offset:27648
	global_load_dwordx4 v[116:119], v[134:135], off offset:896
	v_mfma_f32_32x32x16_bf16 v[4:19], v[148:151], v[152:155], v[4:19]
	s_waitcnt vmcnt(13)
	ds_write_b128 v183, v[128:131] offset:32256
	global_load_dwordx4 v[120:123], v[176:177], off offset:896
	s_waitcnt lgkmcnt(5)
	v_mfma_f32_32x32x16_bf16 v[52:67], v[160:163], v[156:159], v[52:67]
	global_load_dwordx4 v[124:127], v[178:179], off offset:896
	s_waitcnt lgkmcnt(4)
	v_mfma_f32_32x32x16_bf16 v[36:51], v[164:167], v[156:159], v[36:51]
	global_load_dwordx4 v[128:131], v[180:181], off offset:896
	s_waitcnt lgkmcnt(3)
	v_mfma_f32_32x32x16_bf16 v[20:35], v[160:163], v[168:171], v[20:35]
	v_mfma_f32_32x32x16_bf16 v[4:19], v[164:167], v[168:171], v[4:19]
	s_setprio 0
	s_waitcnt lgkmcnt(0)
	s_barrier
	ds_read_b128 v[140:143], v184 offset:36864
	ds_read_b128 v[144:147], v185 offset:55296
	ds_read_b128 v[148:151], v185 offset:59904
	ds_read_b128 v[152:155], v184 offset:41472
	ds_read_b128 v[156:159], v184 offset:36896
	ds_read_b128 v[160:163], v185 offset:55328
	ds_read_b128 v[164:167], v185 offset:59936
	ds_read_b128 v[168:171], v184 offset:41504
	s_setprio 1
	s_waitcnt lgkmcnt(6)
	v_mfma_f32_32x32x16_bf16 v[52:67], v[144:147], v[140:143], v[52:67]
	s_waitcnt vmcnt(15)
	ds_write_b128 v182, v[68:71]
	s_waitcnt lgkmcnt(6)
	v_mfma_f32_32x32x16_bf16 v[36:51], v[148:151], v[140:143], v[36:51]
	s_waitcnt vmcnt(14)
	ds_write_b128 v182, v[72:75] offset:4608
	s_waitcnt lgkmcnt(6)
	v_mfma_f32_32x32x16_bf16 v[20:35], v[144:147], v[152:155], v[20:35]
	s_waitcnt vmcnt(13)
	ds_write_b128 v182, v[76:79] offset:9216
	global_load_dwordx4 v[68:71], v[132:133], off offset:1024
	v_mfma_f32_32x32x16_bf16 v[4:19], v[148:151], v[152:155], v[4:19]
	ds_read_b128 v[140:143], v184 offset:36928
	ds_read_b128 v[144:147], v185 offset:55360
	s_waitcnt lgkmcnt(7)
	v_mfma_f32_32x32x16_bf16 v[52:67], v[160:163], v[156:159], v[52:67]
	ds_read_b128 v[148:151], v185 offset:59968
	ds_read_b128 v[152:155], v184 offset:41536
	s_waitcnt lgkmcnt(8)
	v_mfma_f32_32x32x16_bf16 v[36:51], v[164:167], v[156:159], v[36:51]
	s_waitcnt vmcnt(13)
	ds_write_b128 v182, v[80:83] offset:13824
	global_load_dwordx4 v[72:75], v[138:139], off offset:1024
	s_waitcnt lgkmcnt(8)
	v_mfma_f32_32x32x16_bf16 v[20:35], v[160:163], v[168:171], v[20:35]
	s_waitcnt vmcnt(13)
	ds_write_b128 v182, v[84:87] offset:18432
	global_load_dwordx4 v[76:79], v[172:173], off offset:1024
	v_mfma_f32_32x32x16_bf16 v[4:19], v[164:167], v[168:171], v[4:19]
	ds_read_b128 v[156:159], v184 offset:36960
	ds_read_b128 v[160:163], v185 offset:55392
	s_waitcnt lgkmcnt(6)
	v_mfma_f32_32x32x16_bf16 v[52:67], v[144:147], v[140:143], v[52:67]
	ds_read_b128 v[164:167], v185 offset:60000
	ds_read_b128 v[168:171], v184 offset:41568
	s_waitcnt lgkmcnt(7)
	v_mfma_f32_32x32x16_bf16 v[36:51], v[148:151], v[140:143], v[36:51]
	s_waitcnt vmcnt(13)
	ds_write_b128 v182, v[88:91] offset:23040
	global_load_dwordx4 v[80:83], v[174:175], off offset:1024
	s_waitcnt lgkmcnt(7)
	v_mfma_f32_32x32x16_bf16 v[20:35], v[144:147], v[152:155], v[20:35]
	s_waitcnt vmcnt(13)
	ds_write_b128 v182, v[92:95] offset:27648
	global_load_dwordx4 v[84:87], v[134:135], off offset:1024
	v_mfma_f32_32x32x16_bf16 v[4:19], v[148:151], v[152:155], v[4:19]
	s_waitcnt vmcnt(13)
	ds_write_b128 v182, v[96:99] offset:32256
	global_load_dwordx4 v[88:91], v[176:177], off offset:1024
	s_waitcnt lgkmcnt(5)
	v_mfma_f32_32x32x16_bf16 v[52:67], v[160:163], v[156:159], v[52:67]
	global_load_dwordx4 v[92:95], v[178:179], off offset:1024
	s_waitcnt lgkmcnt(4)
	v_mfma_f32_32x32x16_bf16 v[36:51], v[164:167], v[156:159], v[36:51]
	global_load_dwordx4 v[96:99], v[180:181], off offset:1024
	s_waitcnt lgkmcnt(3)
	v_mfma_f32_32x32x16_bf16 v[20:35], v[160:163], v[168:171], v[20:35]
	v_mfma_f32_32x32x16_bf16 v[4:19], v[164:167], v[168:171], v[4:19]
	s_setprio 0
	s_waitcnt lgkmcnt(0)
	s_barrier
	ds_read_b128 v[140:143], v184
	ds_read_b128 v[144:147], v185 offset:18432
	ds_read_b128 v[148:151], v185 offset:23040
	ds_read_b128 v[152:155], v184 offset:4608
	ds_read_b128 v[156:159], v184 offset:32
	ds_read_b128 v[160:163], v185 offset:18464
	ds_read_b128 v[164:167], v185 offset:23072
	ds_read_b128 v[168:171], v184 offset:4640
	s_setprio 1
	s_waitcnt lgkmcnt(6)
	v_mfma_f32_32x32x16_bf16 v[52:67], v[144:147], v[140:143], v[52:67]
	s_waitcnt vmcnt(15)
	ds_write_b128 v183, v[100:103]
	s_waitcnt lgkmcnt(6)
	v_mfma_f32_32x32x16_bf16 v[36:51], v[148:151], v[140:143], v[36:51]
	s_waitcnt vmcnt(14)
	ds_write_b128 v183, v[104:107] offset:4608
	s_waitcnt lgkmcnt(6)
	v_mfma_f32_32x32x16_bf16 v[20:35], v[144:147], v[152:155], v[20:35]
	s_waitcnt vmcnt(13)
	ds_write_b128 v183, v[108:111] offset:9216
	global_load_dwordx4 v[100:103], v[132:133], off offset:1152
	v_mfma_f32_32x32x16_bf16 v[4:19], v[148:151], v[152:155], v[4:19]
	ds_read_b128 v[140:143], v184 offset:64
	ds_read_b128 v[144:147], v185 offset:18496
	s_waitcnt lgkmcnt(7)
	v_mfma_f32_32x32x16_bf16 v[52:67], v[160:163], v[156:159], v[52:67]
	ds_read_b128 v[148:151], v185 offset:23104
	ds_read_b128 v[152:155], v184 offset:4672
	s_waitcnt lgkmcnt(8)
	v_mfma_f32_32x32x16_bf16 v[36:51], v[164:167], v[156:159], v[36:51]
	s_waitcnt vmcnt(13)
	ds_write_b128 v183, v[112:115] offset:13824
	global_load_dwordx4 v[104:107], v[138:139], off offset:1152
	s_waitcnt lgkmcnt(8)
	v_mfma_f32_32x32x16_bf16 v[20:35], v[160:163], v[168:171], v[20:35]
	s_waitcnt vmcnt(13)
	ds_write_b128 v183, v[116:119] offset:18432
	global_load_dwordx4 v[108:111], v[172:173], off offset:1152
	v_mfma_f32_32x32x16_bf16 v[4:19], v[164:167], v[168:171], v[4:19]
	ds_read_b128 v[156:159], v184 offset:96
	ds_read_b128 v[160:163], v185 offset:18528
	s_waitcnt lgkmcnt(6)
	v_mfma_f32_32x32x16_bf16 v[52:67], v[144:147], v[140:143], v[52:67]
	ds_read_b128 v[164:167], v185 offset:23136
	ds_read_b128 v[168:171], v184 offset:4704
	s_waitcnt lgkmcnt(7)
	v_mfma_f32_32x32x16_bf16 v[36:51], v[148:151], v[140:143], v[36:51]
	s_waitcnt vmcnt(13)
	ds_write_b128 v183, v[120:123] offset:23040
	global_load_dwordx4 v[112:115], v[174:175], off offset:1152
	s_waitcnt lgkmcnt(7)
	v_mfma_f32_32x32x16_bf16 v[20:35], v[144:147], v[152:155], v[20:35]
	s_waitcnt vmcnt(13)
	ds_write_b128 v183, v[124:127] offset:27648
	global_load_dwordx4 v[116:119], v[134:135], off offset:1152
	v_mfma_f32_32x32x16_bf16 v[4:19], v[148:151], v[152:155], v[4:19]
	s_waitcnt vmcnt(13)
	ds_write_b128 v183, v[128:131] offset:32256
	global_load_dwordx4 v[120:123], v[176:177], off offset:1152
	s_waitcnt lgkmcnt(5)
	v_mfma_f32_32x32x16_bf16 v[52:67], v[160:163], v[156:159], v[52:67]
	global_load_dwordx4 v[124:127], v[178:179], off offset:1152
	s_waitcnt lgkmcnt(4)
	v_mfma_f32_32x32x16_bf16 v[36:51], v[164:167], v[156:159], v[36:51]
	global_load_dwordx4 v[128:131], v[180:181], off offset:1152
	s_waitcnt lgkmcnt(3)
	v_mfma_f32_32x32x16_bf16 v[20:35], v[160:163], v[168:171], v[20:35]
	v_mfma_f32_32x32x16_bf16 v[4:19], v[164:167], v[168:171], v[4:19]
	s_setprio 0
	s_waitcnt lgkmcnt(0)
	s_barrier
	ds_read_b128 v[140:143], v184 offset:36864
	ds_read_b128 v[144:147], v185 offset:55296
	ds_read_b128 v[148:151], v185 offset:59904
	ds_read_b128 v[152:155], v184 offset:41472
	ds_read_b128 v[156:159], v184 offset:36896
	ds_read_b128 v[160:163], v185 offset:55328
	ds_read_b128 v[164:167], v185 offset:59936
	ds_read_b128 v[168:171], v184 offset:41504
	s_setprio 1
	s_waitcnt lgkmcnt(6)
	v_mfma_f32_32x32x16_bf16 v[52:67], v[144:147], v[140:143], v[52:67]
	s_waitcnt vmcnt(15)
	ds_write_b128 v182, v[68:71]
	s_waitcnt lgkmcnt(6)
	v_mfma_f32_32x32x16_bf16 v[36:51], v[148:151], v[140:143], v[36:51]
	s_waitcnt vmcnt(14)
	ds_write_b128 v182, v[72:75] offset:4608
	s_waitcnt lgkmcnt(6)
	v_mfma_f32_32x32x16_bf16 v[20:35], v[144:147], v[152:155], v[20:35]
	s_waitcnt vmcnt(13)
	ds_write_b128 v182, v[76:79] offset:9216
	global_load_dwordx4 v[68:71], v[132:133], off offset:1280
	v_mfma_f32_32x32x16_bf16 v[4:19], v[148:151], v[152:155], v[4:19]
	ds_read_b128 v[140:143], v184 offset:36928
	ds_read_b128 v[144:147], v185 offset:55360
	s_waitcnt lgkmcnt(7)
	v_mfma_f32_32x32x16_bf16 v[52:67], v[160:163], v[156:159], v[52:67]
	ds_read_b128 v[148:151], v185 offset:59968
	ds_read_b128 v[152:155], v184 offset:41536
	s_waitcnt lgkmcnt(8)
	v_mfma_f32_32x32x16_bf16 v[36:51], v[164:167], v[156:159], v[36:51]
	s_waitcnt vmcnt(13)
	ds_write_b128 v182, v[80:83] offset:13824
	global_load_dwordx4 v[72:75], v[138:139], off offset:1280
	s_waitcnt lgkmcnt(8)
	v_mfma_f32_32x32x16_bf16 v[20:35], v[160:163], v[168:171], v[20:35]
	s_waitcnt vmcnt(13)
	ds_write_b128 v182, v[84:87] offset:18432
	global_load_dwordx4 v[76:79], v[172:173], off offset:1280
	v_mfma_f32_32x32x16_bf16 v[4:19], v[164:167], v[168:171], v[4:19]
	ds_read_b128 v[156:159], v184 offset:36960
	ds_read_b128 v[160:163], v185 offset:55392
	s_waitcnt lgkmcnt(6)
	v_mfma_f32_32x32x16_bf16 v[52:67], v[144:147], v[140:143], v[52:67]
	ds_read_b128 v[164:167], v185 offset:60000
	ds_read_b128 v[168:171], v184 offset:41568
	s_waitcnt lgkmcnt(7)
	v_mfma_f32_32x32x16_bf16 v[36:51], v[148:151], v[140:143], v[36:51]
	s_waitcnt vmcnt(13)
	ds_write_b128 v182, v[88:91] offset:23040
	global_load_dwordx4 v[80:83], v[174:175], off offset:1280
	s_waitcnt lgkmcnt(7)
	v_mfma_f32_32x32x16_bf16 v[20:35], v[144:147], v[152:155], v[20:35]
	s_waitcnt vmcnt(13)
	ds_write_b128 v182, v[92:95] offset:27648
	global_load_dwordx4 v[84:87], v[134:135], off offset:1280
	v_mfma_f32_32x32x16_bf16 v[4:19], v[148:151], v[152:155], v[4:19]
	s_waitcnt vmcnt(13)
	ds_write_b128 v182, v[96:99] offset:32256
	global_load_dwordx4 v[88:91], v[176:177], off offset:1280
	s_waitcnt lgkmcnt(5)
	v_mfma_f32_32x32x16_bf16 v[52:67], v[160:163], v[156:159], v[52:67]
	global_load_dwordx4 v[92:95], v[178:179], off offset:1280
	s_waitcnt lgkmcnt(4)
	v_mfma_f32_32x32x16_bf16 v[36:51], v[164:167], v[156:159], v[36:51]
	global_load_dwordx4 v[96:99], v[180:181], off offset:1280
	s_waitcnt lgkmcnt(3)
	v_mfma_f32_32x32x16_bf16 v[20:35], v[160:163], v[168:171], v[20:35]
	v_mfma_f32_32x32x16_bf16 v[4:19], v[164:167], v[168:171], v[4:19]
	s_setprio 0
	s_waitcnt lgkmcnt(0)
	s_barrier
	ds_read_b128 v[140:143], v184
	ds_read_b128 v[144:147], v185 offset:18432
	ds_read_b128 v[148:151], v185 offset:23040
	ds_read_b128 v[152:155], v184 offset:4608
	ds_read_b128 v[156:159], v184 offset:32
	ds_read_b128 v[160:163], v185 offset:18464
	ds_read_b128 v[164:167], v185 offset:23072
	ds_read_b128 v[168:171], v184 offset:4640
	s_setprio 1
	s_waitcnt lgkmcnt(6)
	v_mfma_f32_32x32x16_bf16 v[52:67], v[144:147], v[140:143], v[52:67]
	s_waitcnt vmcnt(15)
	ds_write_b128 v183, v[100:103]
	s_waitcnt lgkmcnt(6)
	v_mfma_f32_32x32x16_bf16 v[36:51], v[148:151], v[140:143], v[36:51]
	s_waitcnt vmcnt(14)
	ds_write_b128 v183, v[104:107] offset:4608
	s_waitcnt lgkmcnt(6)
	v_mfma_f32_32x32x16_bf16 v[20:35], v[144:147], v[152:155], v[20:35]
	s_waitcnt vmcnt(13)
	ds_write_b128 v183, v[108:111] offset:9216
	global_load_dwordx4 v[100:103], v[132:133], off offset:1408
	v_mfma_f32_32x32x16_bf16 v[4:19], v[148:151], v[152:155], v[4:19]
	ds_read_b128 v[140:143], v184 offset:64
	ds_read_b128 v[144:147], v185 offset:18496
	s_waitcnt lgkmcnt(7)
	v_mfma_f32_32x32x16_bf16 v[52:67], v[160:163], v[156:159], v[52:67]
	ds_read_b128 v[148:151], v185 offset:23104
	ds_read_b128 v[152:155], v184 offset:4672
	s_waitcnt lgkmcnt(8)
	v_mfma_f32_32x32x16_bf16 v[36:51], v[164:167], v[156:159], v[36:51]
	s_waitcnt vmcnt(13)
	ds_write_b128 v183, v[112:115] offset:13824
	global_load_dwordx4 v[104:107], v[138:139], off offset:1408
	s_waitcnt lgkmcnt(8)
	v_mfma_f32_32x32x16_bf16 v[20:35], v[160:163], v[168:171], v[20:35]
	s_waitcnt vmcnt(13)
	ds_write_b128 v183, v[116:119] offset:18432
	global_load_dwordx4 v[108:111], v[172:173], off offset:1408
	v_mfma_f32_32x32x16_bf16 v[4:19], v[164:167], v[168:171], v[4:19]
	ds_read_b128 v[156:159], v184 offset:96
	ds_read_b128 v[160:163], v185 offset:18528
	s_waitcnt lgkmcnt(6)
	v_mfma_f32_32x32x16_bf16 v[52:67], v[144:147], v[140:143], v[52:67]
	ds_read_b128 v[164:167], v185 offset:23136
	ds_read_b128 v[168:171], v184 offset:4704
	s_waitcnt lgkmcnt(7)
	v_mfma_f32_32x32x16_bf16 v[36:51], v[148:151], v[140:143], v[36:51]
	s_waitcnt vmcnt(13)
	ds_write_b128 v183, v[120:123] offset:23040
	global_load_dwordx4 v[112:115], v[174:175], off offset:1408
	s_waitcnt lgkmcnt(7)
	v_mfma_f32_32x32x16_bf16 v[20:35], v[144:147], v[152:155], v[20:35]
	s_waitcnt vmcnt(13)
	ds_write_b128 v183, v[124:127] offset:27648
	global_load_dwordx4 v[116:119], v[134:135], off offset:1408
	v_mfma_f32_32x32x16_bf16 v[4:19], v[148:151], v[152:155], v[4:19]
	s_waitcnt vmcnt(13)
	ds_write_b128 v183, v[128:131] offset:32256
	global_load_dwordx4 v[120:123], v[176:177], off offset:1408
	s_waitcnt lgkmcnt(5)
	v_mfma_f32_32x32x16_bf16 v[52:67], v[160:163], v[156:159], v[52:67]
	global_load_dwordx4 v[124:127], v[178:179], off offset:1408
	s_waitcnt lgkmcnt(4)
	v_mfma_f32_32x32x16_bf16 v[36:51], v[164:167], v[156:159], v[36:51]
	global_load_dwordx4 v[128:131], v[180:181], off offset:1408
	s_waitcnt lgkmcnt(3)
	v_mfma_f32_32x32x16_bf16 v[20:35], v[160:163], v[168:171], v[20:35]
	v_mfma_f32_32x32x16_bf16 v[4:19], v[164:167], v[168:171], v[4:19]
	s_setprio 0
	s_waitcnt lgkmcnt(0)
	s_barrier
	ds_read_b128 v[140:143], v184 offset:36864
	ds_read_b128 v[144:147], v185 offset:55296
	ds_read_b128 v[148:151], v185 offset:59904
	ds_read_b128 v[152:155], v184 offset:41472
	ds_read_b128 v[156:159], v184 offset:36896
	ds_read_b128 v[160:163], v185 offset:55328
	ds_read_b128 v[164:167], v185 offset:59936
	ds_read_b128 v[168:171], v184 offset:41504
	s_setprio 1
	s_waitcnt lgkmcnt(6)
	v_mfma_f32_32x32x16_bf16 v[52:67], v[144:147], v[140:143], v[52:67]
	s_waitcnt vmcnt(15)
	ds_write_b128 v182, v[68:71]
	s_waitcnt lgkmcnt(6)
	v_mfma_f32_32x32x16_bf16 v[36:51], v[148:151], v[140:143], v[36:51]
	s_waitcnt vmcnt(14)
	ds_write_b128 v182, v[72:75] offset:4608
	s_waitcnt lgkmcnt(6)
	v_mfma_f32_32x32x16_bf16 v[20:35], v[144:147], v[152:155], v[20:35]
	s_waitcnt vmcnt(13)
	ds_write_b128 v182, v[76:79] offset:9216
	global_load_dwordx4 v[68:71], v[132:133], off offset:1536
	v_mfma_f32_32x32x16_bf16 v[4:19], v[148:151], v[152:155], v[4:19]
	ds_read_b128 v[140:143], v184 offset:36928
	ds_read_b128 v[144:147], v185 offset:55360
	s_waitcnt lgkmcnt(7)
	v_mfma_f32_32x32x16_bf16 v[52:67], v[160:163], v[156:159], v[52:67]
	ds_read_b128 v[148:151], v185 offset:59968
	ds_read_b128 v[152:155], v184 offset:41536
	s_waitcnt lgkmcnt(8)
	v_mfma_f32_32x32x16_bf16 v[36:51], v[164:167], v[156:159], v[36:51]
	s_waitcnt vmcnt(13)
	ds_write_b128 v182, v[80:83] offset:13824
	global_load_dwordx4 v[72:75], v[138:139], off offset:1536
	s_waitcnt lgkmcnt(8)
	v_mfma_f32_32x32x16_bf16 v[20:35], v[160:163], v[168:171], v[20:35]
	s_waitcnt vmcnt(13)
	ds_write_b128 v182, v[84:87] offset:18432
	global_load_dwordx4 v[76:79], v[172:173], off offset:1536
	v_mfma_f32_32x32x16_bf16 v[4:19], v[164:167], v[168:171], v[4:19]
	ds_read_b128 v[156:159], v184 offset:36960
	ds_read_b128 v[160:163], v185 offset:55392
	s_waitcnt lgkmcnt(6)
	v_mfma_f32_32x32x16_bf16 v[52:67], v[144:147], v[140:143], v[52:67]
	ds_read_b128 v[164:167], v185 offset:60000
	ds_read_b128 v[168:171], v184 offset:41568
	s_waitcnt lgkmcnt(7)
	v_mfma_f32_32x32x16_bf16 v[36:51], v[148:151], v[140:143], v[36:51]
	s_waitcnt vmcnt(13)
	ds_write_b128 v182, v[88:91] offset:23040
	global_load_dwordx4 v[80:83], v[174:175], off offset:1536
	s_waitcnt lgkmcnt(7)
	v_mfma_f32_32x32x16_bf16 v[20:35], v[144:147], v[152:155], v[20:35]
	s_waitcnt vmcnt(13)
	ds_write_b128 v182, v[92:95] offset:27648
	global_load_dwordx4 v[84:87], v[134:135], off offset:1536
	v_mfma_f32_32x32x16_bf16 v[4:19], v[148:151], v[152:155], v[4:19]
	s_waitcnt vmcnt(13)
	ds_write_b128 v182, v[96:99] offset:32256
	global_load_dwordx4 v[88:91], v[176:177], off offset:1536
	s_waitcnt lgkmcnt(5)
	v_mfma_f32_32x32x16_bf16 v[52:67], v[160:163], v[156:159], v[52:67]
	global_load_dwordx4 v[92:95], v[178:179], off offset:1536
	s_waitcnt lgkmcnt(4)
	v_mfma_f32_32x32x16_bf16 v[36:51], v[164:167], v[156:159], v[36:51]
	global_load_dwordx4 v[96:99], v[180:181], off offset:1536
	s_waitcnt lgkmcnt(3)
	v_mfma_f32_32x32x16_bf16 v[20:35], v[160:163], v[168:171], v[20:35]
	v_mfma_f32_32x32x16_bf16 v[4:19], v[164:167], v[168:171], v[4:19]
	s_setprio 0
	s_waitcnt lgkmcnt(0)
	s_barrier
	ds_read_b128 v[140:143], v184
	ds_read_b128 v[144:147], v185 offset:18432
	ds_read_b128 v[148:151], v185 offset:23040
	ds_read_b128 v[152:155], v184 offset:4608
	ds_read_b128 v[156:159], v184 offset:32
	ds_read_b128 v[160:163], v185 offset:18464
	ds_read_b128 v[164:167], v185 offset:23072
	ds_read_b128 v[168:171], v184 offset:4640
	s_setprio 1
	s_waitcnt lgkmcnt(6)
	v_mfma_f32_32x32x16_bf16 v[52:67], v[144:147], v[140:143], v[52:67]
	s_waitcnt vmcnt(15)
	ds_write_b128 v183, v[100:103]
	s_waitcnt lgkmcnt(6)
	v_mfma_f32_32x32x16_bf16 v[36:51], v[148:151], v[140:143], v[36:51]
	s_waitcnt vmcnt(14)
	ds_write_b128 v183, v[104:107] offset:4608
	s_waitcnt lgkmcnt(6)
	v_mfma_f32_32x32x16_bf16 v[20:35], v[144:147], v[152:155], v[20:35]
	s_waitcnt vmcnt(13)
	ds_write_b128 v183, v[108:111] offset:9216
	global_load_dwordx4 v[100:103], v[132:133], off offset:1664
	v_mfma_f32_32x32x16_bf16 v[4:19], v[148:151], v[152:155], v[4:19]
	ds_read_b128 v[140:143], v184 offset:64
	ds_read_b128 v[144:147], v185 offset:18496
	s_waitcnt lgkmcnt(7)
	v_mfma_f32_32x32x16_bf16 v[52:67], v[160:163], v[156:159], v[52:67]
	ds_read_b128 v[148:151], v185 offset:23104
	ds_read_b128 v[152:155], v184 offset:4672
	s_waitcnt lgkmcnt(8)
	v_mfma_f32_32x32x16_bf16 v[36:51], v[164:167], v[156:159], v[36:51]
	s_waitcnt vmcnt(13)
	ds_write_b128 v183, v[112:115] offset:13824
	global_load_dwordx4 v[104:107], v[138:139], off offset:1664
	s_waitcnt lgkmcnt(8)
	v_mfma_f32_32x32x16_bf16 v[20:35], v[160:163], v[168:171], v[20:35]
	s_waitcnt vmcnt(13)
	ds_write_b128 v183, v[116:119] offset:18432
	global_load_dwordx4 v[108:111], v[172:173], off offset:1664
	v_mfma_f32_32x32x16_bf16 v[4:19], v[164:167], v[168:171], v[4:19]
	ds_read_b128 v[156:159], v184 offset:96
	ds_read_b128 v[160:163], v185 offset:18528
	s_waitcnt lgkmcnt(6)
	v_mfma_f32_32x32x16_bf16 v[52:67], v[144:147], v[140:143], v[52:67]
	ds_read_b128 v[164:167], v185 offset:23136
	ds_read_b128 v[168:171], v184 offset:4704
	s_waitcnt lgkmcnt(7)
	v_mfma_f32_32x32x16_bf16 v[36:51], v[148:151], v[140:143], v[36:51]
	s_waitcnt vmcnt(13)
	ds_write_b128 v183, v[120:123] offset:23040
	global_load_dwordx4 v[112:115], v[174:175], off offset:1664
	s_waitcnt lgkmcnt(7)
	v_mfma_f32_32x32x16_bf16 v[20:35], v[144:147], v[152:155], v[20:35]
	s_waitcnt vmcnt(13)
	ds_write_b128 v183, v[124:127] offset:27648
	global_load_dwordx4 v[116:119], v[134:135], off offset:1664
	v_mfma_f32_32x32x16_bf16 v[4:19], v[148:151], v[152:155], v[4:19]
	s_waitcnt vmcnt(13)
	ds_write_b128 v183, v[128:131] offset:32256
	global_load_dwordx4 v[120:123], v[176:177], off offset:1664
	s_waitcnt lgkmcnt(5)
	v_mfma_f32_32x32x16_bf16 v[52:67], v[160:163], v[156:159], v[52:67]
	global_load_dwordx4 v[124:127], v[178:179], off offset:1664
	s_waitcnt lgkmcnt(4)
	v_mfma_f32_32x32x16_bf16 v[36:51], v[164:167], v[156:159], v[36:51]
	global_load_dwordx4 v[128:131], v[180:181], off offset:1664
	s_waitcnt lgkmcnt(3)
	v_mfma_f32_32x32x16_bf16 v[20:35], v[160:163], v[168:171], v[20:35]
	v_mfma_f32_32x32x16_bf16 v[4:19], v[164:167], v[168:171], v[4:19]
	s_setprio 0
	s_waitcnt lgkmcnt(0)
	s_barrier
	ds_read_b128 v[140:143], v184 offset:36864
	ds_read_b128 v[144:147], v185 offset:55296
	ds_read_b128 v[148:151], v185 offset:59904
	ds_read_b128 v[152:155], v184 offset:41472
	ds_read_b128 v[156:159], v184 offset:36896
	ds_read_b128 v[160:163], v185 offset:55328
	ds_read_b128 v[164:167], v185 offset:59936
	ds_read_b128 v[168:171], v184 offset:41504
	s_setprio 1
	s_waitcnt lgkmcnt(6)
	v_mfma_f32_32x32x16_bf16 v[52:67], v[144:147], v[140:143], v[52:67]
	s_waitcnt vmcnt(15)
	ds_write_b128 v182, v[68:71]
	s_waitcnt lgkmcnt(6)
	v_mfma_f32_32x32x16_bf16 v[36:51], v[148:151], v[140:143], v[36:51]
	s_waitcnt vmcnt(14)
	ds_write_b128 v182, v[72:75] offset:4608
	s_waitcnt lgkmcnt(6)
	v_mfma_f32_32x32x16_bf16 v[20:35], v[144:147], v[152:155], v[20:35]
	s_waitcnt vmcnt(13)
	ds_write_b128 v182, v[76:79] offset:9216
	global_load_dwordx4 v[68:71], v[132:133], off offset:1792
	v_mfma_f32_32x32x16_bf16 v[4:19], v[148:151], v[152:155], v[4:19]
	ds_read_b128 v[140:143], v184 offset:36928
	ds_read_b128 v[144:147], v185 offset:55360
	s_waitcnt lgkmcnt(7)
	v_mfma_f32_32x32x16_bf16 v[52:67], v[160:163], v[156:159], v[52:67]
	ds_read_b128 v[148:151], v185 offset:59968
	ds_read_b128 v[152:155], v184 offset:41536
	s_waitcnt lgkmcnt(8)
	v_mfma_f32_32x32x16_bf16 v[36:51], v[164:167], v[156:159], v[36:51]
	s_waitcnt vmcnt(13)
	ds_write_b128 v182, v[80:83] offset:13824
	global_load_dwordx4 v[72:75], v[138:139], off offset:1792
	s_waitcnt lgkmcnt(8)
	v_mfma_f32_32x32x16_bf16 v[20:35], v[160:163], v[168:171], v[20:35]
	s_waitcnt vmcnt(13)
	ds_write_b128 v182, v[84:87] offset:18432
	global_load_dwordx4 v[76:79], v[172:173], off offset:1792
	v_mfma_f32_32x32x16_bf16 v[4:19], v[164:167], v[168:171], v[4:19]
	ds_read_b128 v[156:159], v184 offset:36960
	ds_read_b128 v[160:163], v185 offset:55392
	s_waitcnt lgkmcnt(6)
	v_mfma_f32_32x32x16_bf16 v[52:67], v[144:147], v[140:143], v[52:67]
	ds_read_b128 v[164:167], v185 offset:60000
	ds_read_b128 v[168:171], v184 offset:41568
	s_waitcnt lgkmcnt(7)
	v_mfma_f32_32x32x16_bf16 v[36:51], v[148:151], v[140:143], v[36:51]
	s_waitcnt vmcnt(13)
	ds_write_b128 v182, v[88:91] offset:23040
	global_load_dwordx4 v[80:83], v[174:175], off offset:1792
	s_waitcnt lgkmcnt(7)
	v_mfma_f32_32x32x16_bf16 v[20:35], v[144:147], v[152:155], v[20:35]
	s_waitcnt vmcnt(13)
	ds_write_b128 v182, v[92:95] offset:27648
	global_load_dwordx4 v[84:87], v[134:135], off offset:1792
	v_mfma_f32_32x32x16_bf16 v[4:19], v[148:151], v[152:155], v[4:19]
	s_waitcnt vmcnt(13)
	ds_write_b128 v182, v[96:99] offset:32256
	global_load_dwordx4 v[88:91], v[176:177], off offset:1792
	s_waitcnt lgkmcnt(5)
	v_mfma_f32_32x32x16_bf16 v[52:67], v[160:163], v[156:159], v[52:67]
	global_load_dwordx4 v[92:95], v[178:179], off offset:1792
	s_waitcnt lgkmcnt(4)
	v_mfma_f32_32x32x16_bf16 v[36:51], v[164:167], v[156:159], v[36:51]
	global_load_dwordx4 v[96:99], v[180:181], off offset:1792
	s_waitcnt lgkmcnt(3)
	v_mfma_f32_32x32x16_bf16 v[20:35], v[160:163], v[168:171], v[20:35]
	v_mfma_f32_32x32x16_bf16 v[4:19], v[164:167], v[168:171], v[4:19]
	s_setprio 0
	s_waitcnt lgkmcnt(0)
	s_barrier
	ds_read_b128 v[140:143], v184
	ds_read_b128 v[144:147], v185 offset:18432
	ds_read_b128 v[148:151], v185 offset:23040
	ds_read_b128 v[152:155], v184 offset:4608
	ds_read_b128 v[156:159], v184 offset:32
	ds_read_b128 v[160:163], v185 offset:18464
	ds_read_b128 v[164:167], v185 offset:23072
	ds_read_b128 v[168:171], v184 offset:4640
	s_setprio 1
	s_waitcnt lgkmcnt(6)
	v_mfma_f32_32x32x16_bf16 v[52:67], v[144:147], v[140:143], v[52:67]
	s_waitcnt vmcnt(15)
	ds_write_b128 v183, v[100:103]
	s_waitcnt lgkmcnt(6)
	v_mfma_f32_32x32x16_bf16 v[36:51], v[148:151], v[140:143], v[36:51]
	s_waitcnt vmcnt(14)
	ds_write_b128 v183, v[104:107] offset:4608
	s_waitcnt lgkmcnt(6)
	v_mfma_f32_32x32x16_bf16 v[20:35], v[144:147], v[152:155], v[20:35]
	s_waitcnt vmcnt(13)
	ds_write_b128 v183, v[108:111] offset:9216
	global_load_dwordx4 v[100:103], v[132:133], off offset:1920
	v_mfma_f32_32x32x16_bf16 v[4:19], v[148:151], v[152:155], v[4:19]
	ds_read_b128 v[140:143], v184 offset:64
	ds_read_b128 v[144:147], v185 offset:18496
	s_waitcnt lgkmcnt(7)
	v_mfma_f32_32x32x16_bf16 v[52:67], v[160:163], v[156:159], v[52:67]
	ds_read_b128 v[148:151], v185 offset:23104
	ds_read_b128 v[152:155], v184 offset:4672
	s_waitcnt lgkmcnt(8)
	v_mfma_f32_32x32x16_bf16 v[36:51], v[164:167], v[156:159], v[36:51]
	s_waitcnt vmcnt(13)
	ds_write_b128 v183, v[112:115] offset:13824
	global_load_dwordx4 v[104:107], v[138:139], off offset:1920
	s_waitcnt lgkmcnt(8)
	v_mfma_f32_32x32x16_bf16 v[20:35], v[160:163], v[168:171], v[20:35]
	s_waitcnt vmcnt(13)
	ds_write_b128 v183, v[116:119] offset:18432
	global_load_dwordx4 v[108:111], v[172:173], off offset:1920
	v_mfma_f32_32x32x16_bf16 v[4:19], v[164:167], v[168:171], v[4:19]
	ds_read_b128 v[156:159], v184 offset:96
	ds_read_b128 v[160:163], v185 offset:18528
	s_waitcnt lgkmcnt(6)
	v_mfma_f32_32x32x16_bf16 v[52:67], v[144:147], v[140:143], v[52:67]
	ds_read_b128 v[164:167], v185 offset:23136
	ds_read_b128 v[168:171], v184 offset:4704
	s_waitcnt lgkmcnt(7)
	v_mfma_f32_32x32x16_bf16 v[36:51], v[148:151], v[140:143], v[36:51]
	s_waitcnt vmcnt(13)
	ds_write_b128 v183, v[120:123] offset:23040
	global_load_dwordx4 v[112:115], v[174:175], off offset:1920
	s_waitcnt lgkmcnt(7)
	v_mfma_f32_32x32x16_bf16 v[20:35], v[144:147], v[152:155], v[20:35]
	s_waitcnt vmcnt(13)
	ds_write_b128 v183, v[124:127] offset:27648
	global_load_dwordx4 v[116:119], v[134:135], off offset:1920
	v_mfma_f32_32x32x16_bf16 v[4:19], v[148:151], v[152:155], v[4:19]
	s_waitcnt vmcnt(13)
	ds_write_b128 v183, v[128:131] offset:32256
	global_load_dwordx4 v[120:123], v[176:177], off offset:1920
	s_waitcnt lgkmcnt(5)
	v_mfma_f32_32x32x16_bf16 v[52:67], v[160:163], v[156:159], v[52:67]
	global_load_dwordx4 v[124:127], v[178:179], off offset:1920
	s_waitcnt lgkmcnt(4)
	v_mfma_f32_32x32x16_bf16 v[36:51], v[164:167], v[156:159], v[36:51]
	global_load_dwordx4 v[128:131], v[180:181], off offset:1920
	s_waitcnt lgkmcnt(3)
	v_mfma_f32_32x32x16_bf16 v[20:35], v[160:163], v[168:171], v[20:35]
	v_mfma_f32_32x32x16_bf16 v[4:19], v[164:167], v[168:171], v[4:19]
	s_setprio 0
	s_waitcnt lgkmcnt(0)
	s_barrier
	ds_read_b128 v[140:143], v184 offset:36864
	ds_read_b128 v[144:147], v185 offset:55296
	ds_read_b128 v[148:151], v185 offset:59904
	ds_read_b128 v[152:155], v184 offset:41472
	ds_read_b128 v[156:159], v184 offset:36896
	ds_read_b128 v[160:163], v185 offset:55328
	ds_read_b128 v[164:167], v185 offset:59936
	ds_read_b128 v[168:171], v184 offset:41504
	s_setprio 1
	s_waitcnt lgkmcnt(6)
	v_mfma_f32_32x32x16_bf16 v[52:67], v[144:147], v[140:143], v[52:67]
	s_waitcnt vmcnt(15)
	ds_write_b128 v182, v[68:71]
	s_waitcnt lgkmcnt(6)
	v_mfma_f32_32x32x16_bf16 v[36:51], v[148:151], v[140:143], v[36:51]
	s_waitcnt vmcnt(14)
	ds_write_b128 v182, v[72:75] offset:4608
	s_waitcnt lgkmcnt(6)
	v_mfma_f32_32x32x16_bf16 v[20:35], v[144:147], v[152:155], v[20:35]
	s_waitcnt vmcnt(13)
	ds_write_b128 v182, v[76:79] offset:9216
	v_mfma_f32_32x32x16_bf16 v[4:19], v[148:151], v[152:155], v[4:19]
	ds_read_b128 v[140:143], v184 offset:36928
	ds_read_b128 v[144:147], v185 offset:55360
	s_waitcnt lgkmcnt(7)
	v_mfma_f32_32x32x16_bf16 v[52:67], v[160:163], v[156:159], v[52:67]
	ds_read_b128 v[148:151], v185 offset:59968
	ds_read_b128 v[152:155], v184 offset:41536
	s_waitcnt lgkmcnt(8)
	v_mfma_f32_32x32x16_bf16 v[36:51], v[164:167], v[156:159], v[36:51]
	s_waitcnt vmcnt(12)
	ds_write_b128 v182, v[80:83] offset:13824
	s_waitcnt lgkmcnt(8)
	v_mfma_f32_32x32x16_bf16 v[20:35], v[160:163], v[168:171], v[20:35]
	s_waitcnt vmcnt(11)
	ds_write_b128 v182, v[84:87] offset:18432
	v_mfma_f32_32x32x16_bf16 v[4:19], v[164:167], v[168:171], v[4:19]
	ds_read_b128 v[156:159], v184 offset:36960
	ds_read_b128 v[160:163], v185 offset:55392
	s_waitcnt lgkmcnt(6)
	v_mfma_f32_32x32x16_bf16 v[52:67], v[144:147], v[140:143], v[52:67]
	ds_read_b128 v[164:167], v185 offset:60000
	ds_read_b128 v[168:171], v184 offset:41568
	s_waitcnt lgkmcnt(7)
	v_mfma_f32_32x32x16_bf16 v[36:51], v[148:151], v[140:143], v[36:51]
	s_waitcnt vmcnt(10)
	ds_write_b128 v182, v[88:91] offset:23040
	s_waitcnt lgkmcnt(7)
	v_mfma_f32_32x32x16_bf16 v[20:35], v[144:147], v[152:155], v[20:35]
	s_waitcnt vmcnt(9)
	ds_write_b128 v182, v[92:95] offset:27648
	v_mfma_f32_32x32x16_bf16 v[4:19], v[148:151], v[152:155], v[4:19]
	s_waitcnt vmcnt(8)
	ds_write_b128 v182, v[96:99] offset:32256
	s_waitcnt lgkmcnt(5)
	v_mfma_f32_32x32x16_bf16 v[52:67], v[160:163], v[156:159], v[52:67]
	s_waitcnt lgkmcnt(4)
	v_mfma_f32_32x32x16_bf16 v[36:51], v[164:167], v[156:159], v[36:51]
	s_waitcnt lgkmcnt(3)
	v_mfma_f32_32x32x16_bf16 v[20:35], v[160:163], v[168:171], v[20:35]
	v_mfma_f32_32x32x16_bf16 v[4:19], v[164:167], v[168:171], v[4:19]
	s_setprio 0
	s_waitcnt lgkmcnt(0)
	s_barrier
	ds_read_b128 v[140:143], v184
	ds_read_b128 v[144:147], v185 offset:18432
	ds_read_b128 v[148:151], v185 offset:23040
	ds_read_b128 v[152:155], v184 offset:4608
	ds_read_b128 v[156:159], v184 offset:32
	ds_read_b128 v[160:163], v185 offset:18464
	ds_read_b128 v[164:167], v185 offset:23072
	ds_read_b128 v[168:171], v184 offset:4640
	s_setprio 1
	s_waitcnt lgkmcnt(6)
	v_mfma_f32_32x32x16_bf16 v[52:67], v[144:147], v[140:143], v[52:67]
	s_waitcnt vmcnt(7)
	ds_write_b128 v183, v[100:103]
	s_waitcnt lgkmcnt(6)
	v_mfma_f32_32x32x16_bf16 v[36:51], v[148:151], v[140:143], v[36:51]
	s_waitcnt vmcnt(6)
	ds_write_b128 v183, v[104:107] offset:4608
	s_waitcnt lgkmcnt(6)
	v_mfma_f32_32x32x16_bf16 v[20:35], v[144:147], v[152:155], v[20:35]
	s_waitcnt vmcnt(5)
	ds_write_b128 v183, v[108:111] offset:9216
	v_mfma_f32_32x32x16_bf16 v[4:19], v[148:151], v[152:155], v[4:19]
	ds_read_b128 v[140:143], v184 offset:64
	ds_read_b128 v[144:147], v185 offset:18496
	s_waitcnt lgkmcnt(7)
	v_mfma_f32_32x32x16_bf16 v[52:67], v[160:163], v[156:159], v[52:67]
	ds_read_b128 v[148:151], v185 offset:23104
	ds_read_b128 v[152:155], v184 offset:4672
	s_waitcnt lgkmcnt(8)
	v_mfma_f32_32x32x16_bf16 v[36:51], v[164:167], v[156:159], v[36:51]
	s_waitcnt vmcnt(4)
	ds_write_b128 v183, v[112:115] offset:13824
	s_waitcnt lgkmcnt(8)
	v_mfma_f32_32x32x16_bf16 v[20:35], v[160:163], v[168:171], v[20:35]
	s_waitcnt vmcnt(3)
	ds_write_b128 v183, v[116:119] offset:18432
	v_mfma_f32_32x32x16_bf16 v[4:19], v[164:167], v[168:171], v[4:19]
	ds_read_b128 v[156:159], v184 offset:96
	ds_read_b128 v[160:163], v185 offset:18528
	s_waitcnt lgkmcnt(6)
	v_mfma_f32_32x32x16_bf16 v[52:67], v[144:147], v[140:143], v[52:67]
	ds_read_b128 v[164:167], v185 offset:23136
	ds_read_b128 v[168:171], v184 offset:4704
	s_waitcnt lgkmcnt(7)
	v_mfma_f32_32x32x16_bf16 v[36:51], v[148:151], v[140:143], v[36:51]
	s_waitcnt vmcnt(2)
	ds_write_b128 v183, v[120:123] offset:23040
	s_waitcnt lgkmcnt(7)
	v_mfma_f32_32x32x16_bf16 v[20:35], v[144:147], v[152:155], v[20:35]
	s_waitcnt vmcnt(1)
	ds_write_b128 v183, v[124:127] offset:27648
	v_mfma_f32_32x32x16_bf16 v[4:19], v[148:151], v[152:155], v[4:19]
	s_waitcnt vmcnt(0)
	ds_write_b128 v183, v[128:131] offset:32256
	s_waitcnt lgkmcnt(5)
	v_mfma_f32_32x32x16_bf16 v[52:67], v[160:163], v[156:159], v[52:67]
	s_waitcnt lgkmcnt(4)
	v_mfma_f32_32x32x16_bf16 v[36:51], v[164:167], v[156:159], v[36:51]
	s_waitcnt lgkmcnt(3)
	v_mfma_f32_32x32x16_bf16 v[20:35], v[160:163], v[168:171], v[20:35]
	v_mfma_f32_32x32x16_bf16 v[4:19], v[164:167], v[168:171], v[4:19]
	s_setprio 0
	s_waitcnt lgkmcnt(0)
	s_barrier
	ds_read_b128 v[140:143], v184 offset:36864
	ds_read_b128 v[144:147], v185 offset:55296
	ds_read_b128 v[148:151], v185 offset:59904
	ds_read_b128 v[152:155], v184 offset:41472
	ds_read_b128 v[156:159], v184 offset:36896
	ds_read_b128 v[160:163], v185 offset:55328
	ds_read_b128 v[164:167], v185 offset:59936
	ds_read_b128 v[168:171], v184 offset:41504
	s_setprio 1
	s_waitcnt lgkmcnt(6)
	v_mfma_f32_32x32x16_bf16 v[52:67], v[144:147], v[140:143], v[52:67]
	s_waitcnt lgkmcnt(5)
	v_mfma_f32_32x32x16_bf16 v[36:51], v[148:151], v[140:143], v[36:51]
	s_waitcnt lgkmcnt(4)
	v_mfma_f32_32x32x16_bf16 v[20:35], v[144:147], v[152:155], v[20:35]
	v_mfma_f32_32x32x16_bf16 v[4:19], v[148:151], v[152:155], v[4:19]
	ds_read_b128 v[140:143], v184 offset:36928
	ds_read_b128 v[144:147], v185 offset:55360
	s_waitcnt lgkmcnt(4)
	v_mfma_f32_32x32x16_bf16 v[52:67], v[160:163], v[156:159], v[52:67]
	ds_read_b128 v[148:151], v185 offset:59968
	ds_read_b128 v[152:155], v184 offset:41536
	s_waitcnt lgkmcnt(5)
	v_mfma_f32_32x32x16_bf16 v[36:51], v[164:167], v[156:159], v[36:51]
	s_waitcnt lgkmcnt(4)
	v_mfma_f32_32x32x16_bf16 v[20:35], v[160:163], v[168:171], v[20:35]
	v_mfma_f32_32x32x16_bf16 v[4:19], v[164:167], v[168:171], v[4:19]
	ds_read_b128 v[156:159], v184 offset:36960
	ds_read_b128 v[160:163], v185 offset:55392
	s_waitcnt lgkmcnt(4)
	v_mfma_f32_32x32x16_bf16 v[52:67], v[144:147], v[140:143], v[52:67]
	ds_read_b128 v[164:167], v185 offset:60000
	ds_read_b128 v[168:171], v184 offset:41568
	s_waitcnt lgkmcnt(5)
	v_mfma_f32_32x32x16_bf16 v[36:51], v[148:151], v[140:143], v[36:51]
	s_waitcnt lgkmcnt(4)
	v_mfma_f32_32x32x16_bf16 v[20:35], v[144:147], v[152:155], v[20:35]
	v_mfma_f32_32x32x16_bf16 v[4:19], v[148:151], v[152:155], v[4:19]
	s_waitcnt lgkmcnt(2)
	v_mfma_f32_32x32x16_bf16 v[52:67], v[160:163], v[156:159], v[52:67]
	s_waitcnt lgkmcnt(1)
	v_mfma_f32_32x32x16_bf16 v[36:51], v[164:167], v[156:159], v[36:51]
	s_waitcnt lgkmcnt(0)
	v_mfma_f32_32x32x16_bf16 v[20:35], v[160:163], v[168:171], v[20:35]
	v_mfma_f32_32x32x16_bf16 v[4:19], v[164:167], v[168:171], v[4:19]
	s_setprio 0
	s_nop 7
	s_nop 4
	s_barrier
	s_load_dword s34, s[62:63], 0x0
	s_waitcnt lgkmcnt(0)
	s_add_i32 s34, s34, s21
	s_cmpk_gt_i32 s34, 0xaff
	s_cselect_b64 s[18:19], -1, 0
	s_and_b64 vcc, exec, s[18:19]
	s_cbranch_vccnz .LBB0_22
	s_lshl_b32 s20, s34, 18
	v_readlane_b32 s24, v252, 47
	v_mov_b32_e32 v2, v0
	s_and_b32 s20, s20, 0xfc0000
	v_readlane_b32 s30, v252, 53
	v_readlane_b32 s31, v252, 54
	v_ashrrev_i32_e32 v68, 3, v2
	s_add_u32 s22, s30, s20
	v_ashrrev_i32_e32 v69, 31, v68
	s_addc_u32 s23, s31, 0
	v_lshlrev_b64 v[68:69], 11, v[68:69]
	v_lshlrev_b32_e32 v2, 4, v2
	v_lshl_add_u64 v[70:71], s[22:23], 0, v[68:69]
	v_and_b32_e32 v2, 0x70, v2
	v_readlane_b32 s25, v252, 48
	s_ashr_i32 s24, s34, 6
	v_lshl_add_u64 v[132:133], v[70:71], 0, v[2:3]
	s_ashr_i32 s25, s24, 31
	v_add_co_u32_e32 v76, vcc, s33, v132
	s_lshl_b64 s[24:25], s[24:25], 17
	s_nop 0
	v_addc_co_u32_e32 v77, vcc, 0, v133, vcc
	s_add_u32 s24, s37, s24
	v_add_co_u32_e32 v80, vcc, s78, v132
	s_addc_u32 s25, s40, s25
	s_nop 0
	v_addc_co_u32_e32 v81, vcc, 0, v133, vcc
	v_lshl_add_u64 v[68:69], s[24:25], 0, v[68:69]
	v_add_co_u32_e32 v84, vcc, s79, v132
	v_lshl_add_u64 v[134:135], v[68:69], 0, v[2:3]
	s_nop 0
	v_addc_co_u32_e32 v85, vcc, 0, v133, vcc
	v_add_co_u32_e32 v92, vcc, s33, v134
	v_readlane_b32 s26, v252, 49
	s_nop 0
	v_addc_co_u32_e32 v93, vcc, 0, v135, vcc
	v_add_co_u32_e32 v96, vcc, 0x580000, v134
	v_readlane_b32 s27, v252, 50
	s_nop 0
	v_addc_co_u32_e32 v97, vcc, 0, v135, vcc
	v_add_co_u32_e32 v128, vcc, 0x590000, v134
	v_readlane_b32 s28, v252, 51
	s_nop 0
	v_addc_co_u32_e32 v129, vcc, 0, v135, vcc
	global_load_dwordx4 v[68:71], v[132:133], off
	global_load_dwordx4 v[100:103], v[132:133], off offset:128
	global_load_dwordx4 v[72:75], v[76:77], off
	global_load_dwordx4 v[104:107], v[76:77], off offset:128
	s_nop 0
	global_load_dwordx4 v[76:79], v[80:81], off
	global_load_dwordx4 v[108:111], v[80:81], off offset:128
	s_nop 0
	global_load_dwordx4 v[80:83], v[84:85], off
	global_load_dwordx4 v[112:115], v[84:85], off offset:128
	s_nop 0
	global_load_dwordx4 v[84:87], v[134:135], off
	global_load_dwordx4 v[116:119], v[134:135], off offset:128
	global_load_dwordx4 v[88:91], v[92:93], off
	global_load_dwordx4 v[120:123], v[92:93], off offset:128
	s_nop 0
	global_load_dwordx4 v[92:95], v[96:97], off
	global_load_dwordx4 v[124:127], v[96:97], off offset:128
	s_nop 0
	global_load_dwordx4 v[96:99], v[128:129], off
	s_nop 0
	global_load_dwordx4 v[128:131], v[128:129], off offset:128
	v_readlane_b32 s29, v252, 52

.LBB0_300:
	s_and_b32 s0, s76, 0xfffffe00
	s_cmpk_eq_i32 s0, 0xc00
	s_cselect_b64 s[0:1], -1, 0
	s_and_b64 s[0:1], s[26:27], s[0:1]
	s_cmpk_lt_i32 s76, 0xd00
	s_movk_i32 s2, 0xff00
	s_cselect_b32 s2, 0x100, s2
	s_and_b64 s[0:1], s[0:1], exec
	s_cselect_b32 s77, s2, 0
	s_add_i32 s77, s77, s76
	s_cmpk_lt_i32 s77, 0xd00
	s_mov_b64 s[0:1], -1
	s_cbranch_scc0 .LBB0_423
	s_mov_b32 s0, 0x10000
	s_mov_b32 s1, 0
	v_lshl_add_u64 v[134:135], s[0:1], 0, v[148:149]
	s_mov_b32 s0, 0x20000
	s_mov_b32 s1, 0
	v_lshl_add_u64 v[176:177], s[0:1], 0, v[148:149]
	s_mov_b32 s0, 0x30000
	s_mov_b32 s1, 0
	v_lshl_add_u64 v[178:179], s[0:1], 0, v[148:149]
	s_mov_b32 s0, 0x10000
	s_mov_b32 s1, 0
	v_lshl_add_u64 v[180:181], s[0:1], 0, v[150:151]
	s_mov_b32 s0, 0x20000
	s_mov_b32 s1, 0
	v_lshl_add_u64 v[182:183], s[0:1], 0, v[150:151]
	s_mov_b32 s0, 0x30000
	s_mov_b32 s1, 0
	v_lshl_add_u64 v[184:185], s[0:1], 0, v[150:151]
	v_lshrrev_b32_e32 v196, 3, v0
	v_lshlrev_b32_e32 v197, 4, v0
	v_mul_u32_u24_e32 v196, 0x90, v196
	v_and_b32_e32 v197, 0x70, v197
	v_add_u32_e32 v186, v196, v197
	v_add_u32_e32 v187, 0x9000, v186
	v_lshrrev_b32_e32 v196, 1, v0
	v_and_b32_e32 v197, 31, v0
	v_and_b32_e32 v214, 16, v196
	v_and_b32_e32 v196, 64, v196
	v_add_u32_e32 v196, v196, v197
	v_mul_u32_u24_e32 v196, 0x90, v196
	v_add_u32_e32 v194, v196, v214
	v_and_b32_e32 v196, 64, v0
	v_add_u32_e32 v196, v196, v197
	v_mul_u32_u24_e32 v196, 0x90, v196
	v_add_u32_e32 v195, v196, v214
	s_barrier
	s_waitcnt vmcnt(15)
	ds_write_b128 v186, v[68:71]
	s_waitcnt vmcnt(13)
	ds_write_b128 v186, v[72:75] offset:4608
	s_waitcnt vmcnt(11)
	ds_write_b128 v186, v[76:79] offset:9216
	s_waitcnt vmcnt(9)
	ds_write_b128 v186, v[80:83] offset:13824
	s_waitcnt vmcnt(7)
	ds_write_b128 v186, v[84:87] offset:18432
	s_waitcnt vmcnt(5)
	ds_write_b128 v186, v[88:91] offset:23040
	s_waitcnt vmcnt(3)
	ds_write_b128 v186, v[92:95] offset:27648
	s_waitcnt vmcnt(1)
	ds_write_b128 v186, v[96:99] offset:32256
	global_load_dwordx4 v[68:71], v[148:149], off offset:256
	global_load_dwordx4 v[72:75], v[134:135], off offset:256
	global_load_dwordx4 v[76:79], v[176:177], off offset:256
	global_load_dwordx4 v[80:83], v[178:179], off offset:256
	global_load_dwordx4 v[84:87], v[150:151], off offset:256
	global_load_dwordx4 v[88:91], v[180:181], off offset:256
	global_load_dwordx4 v[92:95], v[182:183], off offset:256
	global_load_dwordx4 v[96:99], v[184:185], off offset:256
	s_waitcnt lgkmcnt(0)
	s_barrier
	ds_read_b128 v[136:139], v194
	ds_read_b128 v[140:143], v195 offset:18432
	ds_read_b128 v[152:155], v195 offset:23040
	ds_read_b128 v[156:159], v194 offset:4608
	ds_read_b128 v[160:163], v194 offset:32
	ds_read_b128 v[164:167], v195 offset:18464
	ds_read_b128 v[168:171], v195 offset:23072
	ds_read_b128 v[172:175], v194 offset:4640
	s_setprio 1
	s_waitcnt lgkmcnt(6)
	v_mfma_f32_32x32x16_bf16 v[52:67], v[140:143], v[136:139], 0
	ds_write_b128 v187, v[100:103]
	s_waitcnt lgkmcnt(6)
	v_mfma_f32_32x32x16_bf16 v[36:51], v[152:155], v[136:139], 0
	ds_write_b128 v187, v[104:107] offset:4608
	s_waitcnt lgkmcnt(6)
	v_mfma_f32_32x32x16_bf16 v[20:35], v[140:143], v[156:159], 0
	ds_write_b128 v187, v[108:111] offset:9216
	global_load_dwordx4 v[100:103], v[148:149], off offset:384
	v_mfma_f32_32x32x16_bf16 v[4:19], v[152:155], v[156:159], 0
	ds_read_b128 v[136:139], v194 offset:64
	ds_read_b128 v[140:143], v195 offset:18496
	s_waitcnt lgkmcnt(7)
	v_mfma_f32_32x32x16_bf16 v[52:67], v[164:167], v[160:163], v[52:67]
	ds_read_b128 v[152:155], v195 offset:23104
	ds_read_b128 v[156:159], v194 offset:4672
	s_waitcnt lgkmcnt(8)
	v_mfma_f32_32x32x16_bf16 v[36:51], v[168:171], v[160:163], v[36:51]
	ds_write_b128 v187, v[112:115] offset:13824
	global_load_dwordx4 v[104:107], v[134:135], off offset:384
	s_waitcnt lgkmcnt(8)
	v_mfma_f32_32x32x16_bf16 v[20:35], v[164:167], v[172:175], v[20:35]
	ds_write_b128 v187, v[116:119] offset:18432
	global_load_dwordx4 v[108:111], v[176:177], off offset:384
	v_mfma_f32_32x32x16_bf16 v[4:19], v[168:171], v[172:175], v[4:19]
	ds_read_b128 v[160:163], v194 offset:96
	ds_read_b128 v[164:167], v195 offset:18528
	s_waitcnt lgkmcnt(6)
	v_mfma_f32_32x32x16_bf16 v[52:67], v[140:143], v[136:139], v[52:67]
	ds_read_b128 v[168:171], v195 offset:23136
	ds_read_b128 v[172:175], v194 offset:4704
	s_waitcnt lgkmcnt(7)
	v_mfma_f32_32x32x16_bf16 v[36:51], v[152:155], v[136:139], v[36:51]
	ds_write_b128 v187, v[120:123] offset:23040
	global_load_dwordx4 v[112:115], v[178:179], off offset:384
	s_waitcnt lgkmcnt(7)
	v_mfma_f32_32x32x16_bf16 v[20:35], v[140:143], v[156:159], v[20:35]
	ds_write_b128 v187, v[124:127] offset:27648
	global_load_dwordx4 v[116:119], v[150:151], off offset:384
	v_mfma_f32_32x32x16_bf16 v[4:19], v[152:155], v[156:159], v[4:19]
	s_waitcnt vmcnt(13)
	ds_write_b128 v187, v[128:131] offset:32256
	global_load_dwordx4 v[120:123], v[180:181], off offset:384
	s_waitcnt lgkmcnt(5)
	v_mfma_f32_32x32x16_bf16 v[52:67], v[164:167], v[160:163], v[52:67]
	global_load_dwordx4 v[124:127], v[182:183], off offset:384
	s_waitcnt lgkmcnt(4)
	v_mfma_f32_32x32x16_bf16 v[36:51], v[168:171], v[160:163], v[36:51]
	global_load_dwordx4 v[128:131], v[184:185], off offset:384
	s_waitcnt lgkmcnt(3)
	v_mfma_f32_32x32x16_bf16 v[20:35], v[164:167], v[172:175], v[20:35]
	v_mfma_f32_32x32x16_bf16 v[4:19], v[168:171], v[172:175], v[4:19]
	s_setprio 0
	s_waitcnt lgkmcnt(0)
	s_barrier
	ds_read_b128 v[136:139], v194 offset:36864
	ds_read_b128 v[140:143], v195 offset:55296
	ds_read_b128 v[152:155], v195 offset:59904
	ds_read_b128 v[156:159], v194 offset:41472
	ds_read_b128 v[160:163], v194 offset:36896
	ds_read_b128 v[164:167], v195 offset:55328
	ds_read_b128 v[168:171], v195 offset:59936
	ds_read_b128 v[172:175], v194 offset:41504
	s_setprio 1
	s_waitcnt lgkmcnt(6)
	v_mfma_f32_32x32x16_bf16 v[52:67], v[140:143], v[136:139], v[52:67]
	s_waitcnt vmcnt(15)
	ds_write_b128 v186, v[68:71]
	s_waitcnt lgkmcnt(6)
	v_mfma_f32_32x32x16_bf16 v[36:51], v[152:155], v[136:139], v[36:51]
	s_waitcnt vmcnt(14)
	ds_write_b128 v186, v[72:75] offset:4608
	s_waitcnt lgkmcnt(6)
	v_mfma_f32_32x32x16_bf16 v[20:35], v[140:143], v[156:159], v[20:35]
	s_waitcnt vmcnt(13)
	ds_write_b128 v186, v[76:79] offset:9216
	global_load_dwordx4 v[68:71], v[148:149], off offset:512
	v_mfma_f32_32x32x16_bf16 v[4:19], v[152:155], v[156:159], v[4:19]
	ds_read_b128 v[136:139], v194 offset:36928
	ds_read_b128 v[140:143], v195 offset:55360
	s_waitcnt lgkmcnt(7)
	v_mfma_f32_32x32x16_bf16 v[52:67], v[164:167], v[160:163], v[52:67]
	ds_read_b128 v[152:155], v195 offset:59968
	ds_read_b128 v[156:159], v194 offset:41536
	s_waitcnt lgkmcnt(8)
	v_mfma_f32_32x32x16_bf16 v[36:51], v[168:171], v[160:163], v[36:51]
	s_waitcnt vmcnt(13)
	ds_write_b128 v186, v[80:83] offset:13824
	global_load_dwordx4 v[72:75], v[134:135], off offset:512
	s_waitcnt lgkmcnt(8)
	v_mfma_f32_32x32x16_bf16 v[20:35], v[164:167], v[172:175], v[20:35]
	s_waitcnt vmcnt(13)
	ds_write_b128 v186, v[84:87] offset:18432
	global_load_dwordx4 v[76:79], v[176:177], off offset:512
	v_mfma_f32_32x32x16_bf16 v[4:19], v[168:171], v[172:175], v[4:19]
	ds_read_b128 v[160:163], v194 offset:36960
	ds_read_b128 v[164:167], v195 offset:55392
	s_waitcnt lgkmcnt(6)
	v_mfma_f32_32x32x16_bf16 v[52:67], v[140:143], v[136:139], v[52:67]
	ds_read_b128 v[168:171], v195 offset:60000
	ds_read_b128 v[172:175], v194 offset:41568
	s_waitcnt lgkmcnt(7)
	v_mfma_f32_32x32x16_bf16 v[36:51], v[152:155], v[136:139], v[36:51]
	s_waitcnt vmcnt(13)
	ds_write_b128 v186, v[88:91] offset:23040
	global_load_dwordx4 v[80:83], v[178:179], off offset:512
	s_waitcnt lgkmcnt(7)
	v_mfma_f32_32x32x16_bf16 v[20:35], v[140:143], v[156:159], v[20:35]
	s_waitcnt vmcnt(13)
	ds_write_b128 v186, v[92:95] offset:27648
	global_load_dwordx4 v[84:87], v[150:151], off offset:512
	v_mfma_f32_32x32x16_bf16 v[4:19], v[152:155], v[156:159], v[4:19]
	s_waitcnt vmcnt(13)
	ds_write_b128 v186, v[96:99] offset:32256
	global_load_dwordx4 v[88:91], v[180:181], off offset:512
	s_waitcnt lgkmcnt(5)
	v_mfma_f32_32x32x16_bf16 v[52:67], v[164:167], v[160:163], v[52:67]
	global_load_dwordx4 v[92:95], v[182:183], off offset:512
	s_waitcnt lgkmcnt(4)
	v_mfma_f32_32x32x16_bf16 v[36:51], v[168:171], v[160:163], v[36:51]
	global_load_dwordx4 v[96:99], v[184:185], off offset:512
	s_waitcnt lgkmcnt(3)
	v_mfma_f32_32x32x16_bf16 v[20:35], v[164:167], v[172:175], v[20:35]
	v_mfma_f32_32x32x16_bf16 v[4:19], v[168:171], v[172:175], v[4:19]
	s_setprio 0
	s_waitcnt lgkmcnt(0)
	s_barrier
	ds_read_b128 v[136:139], v194
	ds_read_b128 v[140:143], v195 offset:18432
	ds_read_b128 v[152:155], v195 offset:23040
	ds_read_b128 v[156:159], v194 offset:4608
	ds_read_b128 v[160:163], v194 offset:32
	ds_read_b128 v[164:167], v195 offset:18464
	ds_read_b128 v[168:171], v195 offset:23072
	ds_read_b128 v[172:175], v194 offset:4640
	s_setprio 1
	s_waitcnt lgkmcnt(6)
	v_mfma_f32_32x32x16_bf16 v[52:67], v[140:143], v[136:139], v[52:67]
	s_waitcnt vmcnt(15)
	ds_write_b128 v187, v[100:103]
	s_waitcnt lgkmcnt(6)
	v_mfma_f32_32x32x16_bf16 v[36:51], v[152:155], v[136:139], v[36:51]
	s_waitcnt vmcnt(14)
	ds_write_b128 v187, v[104:107] offset:4608
	s_waitcnt lgkmcnt(6)
	v_mfma_f32_32x32x16_bf16 v[20:35], v[140:143], v[156:159], v[20:35]
	s_waitcnt vmcnt(13)
	ds_write_b128 v187, v[108:111] offset:9216
	global_load_dwordx4 v[100:103], v[148:149], off offset:640
	v_mfma_f32_32x32x16_bf16 v[4:19], v[152:155], v[156:159], v[4:19]
	ds_read_b128 v[136:139], v194 offset:64
	ds_read_b128 v[140:143], v195 offset:18496
	s_waitcnt lgkmcnt(7)
	v_mfma_f32_32x32x16_bf16 v[52:67], v[164:167], v[160:163], v[52:67]
	ds_read_b128 v[152:155], v195 offset:23104
	ds_read_b128 v[156:159], v194 offset:4672
	s_waitcnt lgkmcnt(8)
	v_mfma_f32_32x32x16_bf16 v[36:51], v[168:171], v[160:163], v[36:51]
	s_waitcnt vmcnt(13)
	ds_write_b128 v187, v[112:115] offset:13824
	global_load_dwordx4 v[104:107], v[134:135], off offset:640
	s_waitcnt lgkmcnt(8)
	v_mfma_f32_32x32x16_bf16 v[20:35], v[164:167], v[172:175], v[20:35]
	s_waitcnt vmcnt(13)
	ds_write_b128 v187, v[116:119] offset:18432
	global_load_dwordx4 v[108:111], v[176:177], off offset:640
	v_mfma_f32_32x32x16_bf16 v[4:19], v[168:171], v[172:175], v[4:19]
	ds_read_b128 v[160:163], v194 offset:96
	ds_read_b128 v[164:167], v195 offset:18528
	s_waitcnt lgkmcnt(6)
	v_mfma_f32_32x32x16_bf16 v[52:67], v[140:143], v[136:139], v[52:67]
	ds_read_b128 v[168:171], v195 offset:23136
	ds_read_b128 v[172:175], v194 offset:4704
	s_waitcnt lgkmcnt(7)
	v_mfma_f32_32x32x16_bf16 v[36:51], v[152:155], v[136:139], v[36:51]
	s_waitcnt vmcnt(13)
	ds_write_b128 v187, v[120:123] offset:23040
	global_load_dwordx4 v[112:115], v[178:179], off offset:640
	s_waitcnt lgkmcnt(7)
	v_mfma_f32_32x32x16_bf16 v[20:35], v[140:143], v[156:159], v[20:35]
	s_waitcnt vmcnt(13)
	ds_write_b128 v187, v[124:127] offset:27648
	global_load_dwordx4 v[116:119], v[150:151], off offset:640
	v_mfma_f32_32x32x16_bf16 v[4:19], v[152:155], v[156:159], v[4:19]
	s_waitcnt vmcnt(13)
	ds_write_b128 v187, v[128:131] offset:32256
	global_load_dwordx4 v[120:123], v[180:181], off offset:640
	s_waitcnt lgkmcnt(5)
	v_mfma_f32_32x32x16_bf16 v[52:67], v[164:167], v[160:163], v[52:67]
	global_load_dwordx4 v[124:127], v[182:183], off offset:640
	s_waitcnt lgkmcnt(4)
	v_mfma_f32_32x32x16_bf16 v[36:51], v[168:171], v[160:163], v[36:51]
	global_load_dwordx4 v[128:131], v[184:185], off offset:640
	s_waitcnt lgkmcnt(3)
	v_mfma_f32_32x32x16_bf16 v[20:35], v[164:167], v[172:175], v[20:35]
	v_mfma_f32_32x32x16_bf16 v[4:19], v[168:171], v[172:175], v[4:19]
	s_setprio 0
	s_waitcnt lgkmcnt(0)
	s_barrier
	ds_read_b128 v[136:139], v194 offset:36864
	ds_read_b128 v[140:143], v195 offset:55296
	ds_read_b128 v[152:155], v195 offset:59904
	ds_read_b128 v[156:159], v194 offset:41472
	ds_read_b128 v[160:163], v194 offset:36896
	ds_read_b128 v[164:167], v195 offset:55328
	ds_read_b128 v[168:171], v195 offset:59936
	ds_read_b128 v[172:175], v194 offset:41504
	s_setprio 1
	s_waitcnt lgkmcnt(6)
	v_mfma_f32_32x32x16_bf16 v[52:67], v[140:143], v[136:139], v[52:67]
	s_waitcnt vmcnt(15)
	ds_write_b128 v186, v[68:71]
	s_waitcnt lgkmcnt(6)
	v_mfma_f32_32x32x16_bf16 v[36:51], v[152:155], v[136:139], v[36:51]
	s_waitcnt vmcnt(14)
	ds_write_b128 v186, v[72:75] offset:4608
	s_waitcnt lgkmcnt(6)
	v_mfma_f32_32x32x16_bf16 v[20:35], v[140:143], v[156:159], v[20:35]
	s_waitcnt vmcnt(13)
	ds_write_b128 v186, v[76:79] offset:9216
	global_load_dwordx4 v[68:71], v[148:149], off offset:768
	v_mfma_f32_32x32x16_bf16 v[4:19], v[152:155], v[156:159], v[4:19]
	ds_read_b128 v[136:139], v194 offset:36928
	ds_read_b128 v[140:143], v195 offset:55360
	s_waitcnt lgkmcnt(7)
	v_mfma_f32_32x32x16_bf16 v[52:67], v[164:167], v[160:163], v[52:67]
	ds_read_b128 v[152:155], v195 offset:59968
	ds_read_b128 v[156:159], v194 offset:41536
	s_waitcnt lgkmcnt(8)
	v_mfma_f32_32x32x16_bf16 v[36:51], v[168:171], v[160:163], v[36:51]
	s_waitcnt vmcnt(13)
	ds_write_b128 v186, v[80:83] offset:13824
	global_load_dwordx4 v[72:75], v[134:135], off offset:768
	s_waitcnt lgkmcnt(8)
	v_mfma_f32_32x32x16_bf16 v[20:35], v[164:167], v[172:175], v[20:35]
	s_waitcnt vmcnt(13)
	ds_write_b128 v186, v[84:87] offset:18432
	global_load_dwordx4 v[76:79], v[176:177], off offset:768
	v_mfma_f32_32x32x16_bf16 v[4:19], v[168:171], v[172:175], v[4:19]
	ds_read_b128 v[160:163], v194 offset:36960
	ds_read_b128 v[164:167], v195 offset:55392
	s_waitcnt lgkmcnt(6)
	v_mfma_f32_32x32x16_bf16 v[52:67], v[140:143], v[136:139], v[52:67]
	ds_read_b128 v[168:171], v195 offset:60000
	ds_read_b128 v[172:175], v194 offset:41568
	s_waitcnt lgkmcnt(7)
	v_mfma_f32_32x32x16_bf16 v[36:51], v[152:155], v[136:139], v[36:51]
	s_waitcnt vmcnt(13)
	ds_write_b128 v186, v[88:91] offset:23040
	global_load_dwordx4 v[80:83], v[178:179], off offset:768
	s_waitcnt lgkmcnt(7)
	v_mfma_f32_32x32x16_bf16 v[20:35], v[140:143], v[156:159], v[20:35]
	s_waitcnt vmcnt(13)
	ds_write_b128 v186, v[92:95] offset:27648
	global_load_dwordx4 v[84:87], v[150:151], off offset:768
	v_mfma_f32_32x32x16_bf16 v[4:19], v[152:155], v[156:159], v[4:19]
	s_waitcnt vmcnt(13)
	ds_write_b128 v186, v[96:99] offset:32256
	global_load_dwordx4 v[88:91], v[180:181], off offset:768
	s_waitcnt lgkmcnt(5)
	v_mfma_f32_32x32x16_bf16 v[52:67], v[164:167], v[160:163], v[52:67]
	global_load_dwordx4 v[92:95], v[182:183], off offset:768
	s_waitcnt lgkmcnt(4)
	v_mfma_f32_32x32x16_bf16 v[36:51], v[168:171], v[160:163], v[36:51]
	global_load_dwordx4 v[96:99], v[184:185], off offset:768
	s_waitcnt lgkmcnt(3)
	v_mfma_f32_32x32x16_bf16 v[20:35], v[164:167], v[172:175], v[20:35]
	v_mfma_f32_32x32x16_bf16 v[4:19], v[168:171], v[172:175], v[4:19]
	s_setprio 0
	s_waitcnt lgkmcnt(0)
	s_barrier
	ds_read_b128 v[136:139], v194
	ds_read_b128 v[140:143], v195 offset:18432
	ds_read_b128 v[152:155], v195 offset:23040
	ds_read_b128 v[156:159], v194 offset:4608
	ds_read_b128 v[160:163], v194 offset:32
	ds_read_b128 v[164:167], v195 offset:18464
	ds_read_b128 v[168:171], v195 offset:23072
	ds_read_b128 v[172:175], v194 offset:4640
	s_setprio 1
	s_waitcnt lgkmcnt(6)
	v_mfma_f32_32x32x16_bf16 v[52:67], v[140:143], v[136:139], v[52:67]
	s_waitcnt vmcnt(15)
	ds_write_b128 v187, v[100:103]
	s_waitcnt lgkmcnt(6)
	v_mfma_f32_32x32x16_bf16 v[36:51], v[152:155], v[136:139], v[36:51]
	s_waitcnt vmcnt(14)
	ds_write_b128 v187, v[104:107] offset:4608
	s_waitcnt lgkmcnt(6)
	v_mfma_f32_32x32x16_bf16 v[20:35], v[140:143], v[156:159], v[20:35]
	s_waitcnt vmcnt(13)
	ds_write_b128 v187, v[108:111] offset:9216
	global_load_dwordx4 v[100:103], v[148:149], off offset:896
	v_mfma_f32_32x32x16_bf16 v[4:19], v[152:155], v[156:159], v[4:19]
	ds_read_b128 v[136:139], v194 offset:64
	ds_read_b128 v[140:143], v195 offset:18496
	s_waitcnt lgkmcnt(7)
	v_mfma_f32_32x32x16_bf16 v[52:67], v[164:167], v[160:163], v[52:67]
	ds_read_b128 v[152:155], v195 offset:23104
	ds_read_b128 v[156:159], v194 offset:4672
	s_waitcnt lgkmcnt(8)
	v_mfma_f32_32x32x16_bf16 v[36:51], v[168:171], v[160:163], v[36:51]
	s_waitcnt vmcnt(13)
	ds_write_b128 v187, v[112:115] offset:13824
	global_load_dwordx4 v[104:107], v[134:135], off offset:896
	s_waitcnt lgkmcnt(8)
	v_mfma_f32_32x32x16_bf16 v[20:35], v[164:167], v[172:175], v[20:35]
	s_waitcnt vmcnt(13)
	ds_write_b128 v187, v[116:119] offset:18432
	global_load_dwordx4 v[108:111], v[176:177], off offset:896
	v_mfma_f32_32x32x16_bf16 v[4:19], v[168:171], v[172:175], v[4:19]
	ds_read_b128 v[160:163], v194 offset:96
	ds_read_b128 v[164:167], v195 offset:18528
	s_waitcnt lgkmcnt(6)
	v_mfma_f32_32x32x16_bf16 v[52:67], v[140:143], v[136:139], v[52:67]
	ds_read_b128 v[168:171], v195 offset:23136
	ds_read_b128 v[172:175], v194 offset:4704
	s_waitcnt lgkmcnt(7)
	v_mfma_f32_32x32x16_bf16 v[36:51], v[152:155], v[136:139], v[36:51]
	s_waitcnt vmcnt(13)
	ds_write_b128 v187, v[120:123] offset:23040
	global_load_dwordx4 v[112:115], v[178:179], off offset:896
	s_waitcnt lgkmcnt(7)
	v_mfma_f32_32x32x16_bf16 v[20:35], v[140:143], v[156:159], v[20:35]
	s_waitcnt vmcnt(13)
	ds_write_b128 v187, v[124:127] offset:27648
	global_load_dwordx4 v[116:119], v[150:151], off offset:896
	v_mfma_f32_32x32x16_bf16 v[4:19], v[152:155], v[156:159], v[4:19]
	s_waitcnt vmcnt(13)
	ds_write_b128 v187, v[128:131] offset:32256
	global_load_dwordx4 v[120:123], v[180:181], off offset:896
	s_waitcnt lgkmcnt(5)
	v_mfma_f32_32x32x16_bf16 v[52:67], v[164:167], v[160:163], v[52:67]
	global_load_dwordx4 v[124:127], v[182:183], off offset:896
	s_waitcnt lgkmcnt(4)
	v_mfma_f32_32x32x16_bf16 v[36:51], v[168:171], v[160:163], v[36:51]
	global_load_dwordx4 v[128:131], v[184:185], off offset:896
	s_waitcnt lgkmcnt(3)
	v_mfma_f32_32x32x16_bf16 v[20:35], v[164:167], v[172:175], v[20:35]
	v_mfma_f32_32x32x16_bf16 v[4:19], v[168:171], v[172:175], v[4:19]
	s_setprio 0
	s_waitcnt lgkmcnt(0)
	s_barrier
	ds_read_b128 v[136:139], v194 offset:36864
	ds_read_b128 v[140:143], v195 offset:55296
	ds_read_b128 v[152:155], v195 offset:59904
	ds_read_b128 v[156:159], v194 offset:41472
	ds_read_b128 v[160:163], v194 offset:36896
	ds_read_b128 v[164:167], v195 offset:55328
	ds_read_b128 v[168:171], v195 offset:59936
	ds_read_b128 v[172:175], v194 offset:41504
	s_setprio 1
	s_waitcnt lgkmcnt(6)
	v_mfma_f32_32x32x16_bf16 v[52:67], v[140:143], v[136:139], v[52:67]
	s_waitcnt vmcnt(15)
	ds_write_b128 v186, v[68:71]
	s_waitcnt lgkmcnt(6)
	v_mfma_f32_32x32x16_bf16 v[36:51], v[152:155], v[136:139], v[36:51]
	s_waitcnt vmcnt(14)
	ds_write_b128 v186, v[72:75] offset:4608
	s_waitcnt lgkmcnt(6)
	v_mfma_f32_32x32x16_bf16 v[20:35], v[140:143], v[156:159], v[20:35]
	s_waitcnt vmcnt(13)
	ds_write_b128 v186, v[76:79] offset:9216
	global_load_dwordx4 v[68:71], v[148:149], off offset:1024
	v_mfma_f32_32x32x16_bf16 v[4:19], v[152:155], v[156:159], v[4:19]
	ds_read_b128 v[136:139], v194 offset:36928
	ds_read_b128 v[140:143], v195 offset:55360
	s_waitcnt lgkmcnt(7)
	v_mfma_f32_32x32x16_bf16 v[52:67], v[164:167], v[160:163], v[52:67]
	ds_read_b128 v[152:155], v195 offset:59968
	ds_read_b128 v[156:159], v194 offset:41536
	s_waitcnt lgkmcnt(8)
	v_mfma_f32_32x32x16_bf16 v[36:51], v[168:171], v[160:163], v[36:51]
	s_waitcnt vmcnt(13)
	ds_write_b128 v186, v[80:83] offset:13824
	global_load_dwordx4 v[72:75], v[134:135], off offset:1024
	s_waitcnt lgkmcnt(8)
	v_mfma_f32_32x32x16_bf16 v[20:35], v[164:167], v[172:175], v[20:35]
	s_waitcnt vmcnt(13)
	ds_write_b128 v186, v[84:87] offset:18432
	global_load_dwordx4 v[76:79], v[176:177], off offset:1024
	v_mfma_f32_32x32x16_bf16 v[4:19], v[168:171], v[172:175], v[4:19]
	ds_read_b128 v[160:163], v194 offset:36960
	ds_read_b128 v[164:167], v195 offset:55392
	s_waitcnt lgkmcnt(6)
	v_mfma_f32_32x32x16_bf16 v[52:67], v[140:143], v[136:139], v[52:67]
	ds_read_b128 v[168:171], v195 offset:60000
	ds_read_b128 v[172:175], v194 offset:41568
	s_waitcnt lgkmcnt(7)
	v_mfma_f32_32x32x16_bf16 v[36:51], v[152:155], v[136:139], v[36:51]
	s_waitcnt vmcnt(13)
	ds_write_b128 v186, v[88:91] offset:23040
	global_load_dwordx4 v[80:83], v[178:179], off offset:1024
	s_waitcnt lgkmcnt(7)
	v_mfma_f32_32x32x16_bf16 v[20:35], v[140:143], v[156:159], v[20:35]
	s_waitcnt vmcnt(13)
	ds_write_b128 v186, v[92:95] offset:27648
	global_load_dwordx4 v[84:87], v[150:151], off offset:1024
	v_mfma_f32_32x32x16_bf16 v[4:19], v[152:155], v[156:159], v[4:19]
	s_waitcnt vmcnt(13)
	ds_write_b128 v186, v[96:99] offset:32256
	global_load_dwordx4 v[88:91], v[180:181], off offset:1024
	s_waitcnt lgkmcnt(5)
	v_mfma_f32_32x32x16_bf16 v[52:67], v[164:167], v[160:163], v[52:67]
	global_load_dwordx4 v[92:95], v[182:183], off offset:1024
	s_waitcnt lgkmcnt(4)
	v_mfma_f32_32x32x16_bf16 v[36:51], v[168:171], v[160:163], v[36:51]
	global_load_dwordx4 v[96:99], v[184:185], off offset:1024
	s_waitcnt lgkmcnt(3)
	v_mfma_f32_32x32x16_bf16 v[20:35], v[164:167], v[172:175], v[20:35]
	v_mfma_f32_32x32x16_bf16 v[4:19], v[168:171], v[172:175], v[4:19]
	s_setprio 0
	s_waitcnt lgkmcnt(0)
	s_barrier
	ds_read_b128 v[136:139], v194
	ds_read_b128 v[140:143], v195 offset:18432
	ds_read_b128 v[152:155], v195 offset:23040
	ds_read_b128 v[156:159], v194 offset:4608
	ds_read_b128 v[160:163], v194 offset:32
	ds_read_b128 v[164:167], v195 offset:18464
	ds_read_b128 v[168:171], v195 offset:23072
	ds_read_b128 v[172:175], v194 offset:4640
	s_setprio 1
	s_waitcnt lgkmcnt(6)
	v_mfma_f32_32x32x16_bf16 v[52:67], v[140:143], v[136:139], v[52:67]
	s_waitcnt vmcnt(15)
	ds_write_b128 v187, v[100:103]
	s_waitcnt lgkmcnt(6)
	v_mfma_f32_32x32x16_bf16 v[36:51], v[152:155], v[136:139], v[36:51]
	s_waitcnt vmcnt(14)
	ds_write_b128 v187, v[104:107] offset:4608
	s_waitcnt lgkmcnt(6)
	v_mfma_f32_32x32x16_bf16 v[20:35], v[140:143], v[156:159], v[20:35]
	s_waitcnt vmcnt(13)
	ds_write_b128 v187, v[108:111] offset:9216
	global_load_dwordx4 v[100:103], v[148:149], off offset:1152
	v_mfma_f32_32x32x16_bf16 v[4:19], v[152:155], v[156:159], v[4:19]
	ds_read_b128 v[136:139], v194 offset:64
	ds_read_b128 v[140:143], v195 offset:18496
	s_waitcnt lgkmcnt(7)
	v_mfma_f32_32x32x16_bf16 v[52:67], v[164:167], v[160:163], v[52:67]
	ds_read_b128 v[152:155], v195 offset:23104
	ds_read_b128 v[156:159], v194 offset:4672
	s_waitcnt lgkmcnt(8)
	v_mfma_f32_32x32x16_bf16 v[36:51], v[168:171], v[160:163], v[36:51]
	s_waitcnt vmcnt(13)
	ds_write_b128 v187, v[112:115] offset:13824
	global_load_dwordx4 v[104:107], v[134:135], off offset:1152
	s_waitcnt lgkmcnt(8)
	v_mfma_f32_32x32x16_bf16 v[20:35], v[164:167], v[172:175], v[20:35]
	s_waitcnt vmcnt(13)
	ds_write_b128 v187, v[116:119] offset:18432
	global_load_dwordx4 v[108:111], v[176:177], off offset:1152
	v_mfma_f32_32x32x16_bf16 v[4:19], v[168:171], v[172:175], v[4:19]
	ds_read_b128 v[160:163], v194 offset:96
	ds_read_b128 v[164:167], v195 offset:18528
	s_waitcnt lgkmcnt(6)
	v_mfma_f32_32x32x16_bf16 v[52:67], v[140:143], v[136:139], v[52:67]
	ds_read_b128 v[168:171], v195 offset:23136
	ds_read_b128 v[172:175], v194 offset:4704
	s_waitcnt lgkmcnt(7)
	v_mfma_f32_32x32x16_bf16 v[36:51], v[152:155], v[136:139], v[36:51]
	s_waitcnt vmcnt(13)
	ds_write_b128 v187, v[120:123] offset:23040
	global_load_dwordx4 v[112:115], v[178:179], off offset:1152
	s_waitcnt lgkmcnt(7)
	v_mfma_f32_32x32x16_bf16 v[20:35], v[140:143], v[156:159], v[20:35]
	s_waitcnt vmcnt(13)
	ds_write_b128 v187, v[124:127] offset:27648
	global_load_dwordx4 v[116:119], v[150:151], off offset:1152
	v_mfma_f32_32x32x16_bf16 v[4:19], v[152:155], v[156:159], v[4:19]
	s_waitcnt vmcnt(13)
	ds_write_b128 v187, v[128:131] offset:32256
	global_load_dwordx4 v[120:123], v[180:181], off offset:1152
	s_waitcnt lgkmcnt(5)
	v_mfma_f32_32x32x16_bf16 v[52:67], v[164:167], v[160:163], v[52:67]
	global_load_dwordx4 v[124:127], v[182:183], off offset:1152
	s_waitcnt lgkmcnt(4)
	v_mfma_f32_32x32x16_bf16 v[36:51], v[168:171], v[160:163], v[36:51]
	global_load_dwordx4 v[128:131], v[184:185], off offset:1152
	s_waitcnt lgkmcnt(3)
	v_mfma_f32_32x32x16_bf16 v[20:35], v[164:167], v[172:175], v[20:35]
	v_mfma_f32_32x32x16_bf16 v[4:19], v[168:171], v[172:175], v[4:19]
	s_setprio 0
	s_waitcnt lgkmcnt(0)
	s_barrier
	ds_read_b128 v[136:139], v194 offset:36864
	ds_read_b128 v[140:143], v195 offset:55296
	ds_read_b128 v[152:155], v195 offset:59904
	ds_read_b128 v[156:159], v194 offset:41472
	ds_read_b128 v[160:163], v194 offset:36896
	ds_read_b128 v[164:167], v195 offset:55328
	ds_read_b128 v[168:171], v195 offset:59936
	ds_read_b128 v[172:175], v194 offset:41504
	s_setprio 1
	s_waitcnt lgkmcnt(6)
	v_mfma_f32_32x32x16_bf16 v[52:67], v[140:143], v[136:139], v[52:67]
	s_waitcnt vmcnt(15)
	ds_write_b128 v186, v[68:71]
	s_waitcnt lgkmcnt(6)
	v_mfma_f32_32x32x16_bf16 v[36:51], v[152:155], v[136:139], v[36:51]
	s_waitcnt vmcnt(14)
	ds_write_b128 v186, v[72:75] offset:4608
	s_waitcnt lgkmcnt(6)
	v_mfma_f32_32x32x16_bf16 v[20:35], v[140:143], v[156:159], v[20:35]
	s_waitcnt vmcnt(13)
	ds_write_b128 v186, v[76:79] offset:9216
	global_load_dwordx4 v[68:71], v[148:149], off offset:1280
	v_mfma_f32_32x32x16_bf16 v[4:19], v[152:155], v[156:159], v[4:19]
	ds_read_b128 v[136:139], v194 offset:36928
	ds_read_b128 v[140:143], v195 offset:55360
	s_waitcnt lgkmcnt(7)
	v_mfma_f32_32x32x16_bf16 v[52:67], v[164:167], v[160:163], v[52:67]
	ds_read_b128 v[152:155], v195 offset:59968
	ds_read_b128 v[156:159], v194 offset:41536
	s_waitcnt lgkmcnt(8)
	v_mfma_f32_32x32x16_bf16 v[36:51], v[168:171], v[160:163], v[36:51]
	s_waitcnt vmcnt(13)
	ds_write_b128 v186, v[80:83] offset:13824
	global_load_dwordx4 v[72:75], v[134:135], off offset:1280
	s_waitcnt lgkmcnt(8)
	v_mfma_f32_32x32x16_bf16 v[20:35], v[164:167], v[172:175], v[20:35]
	s_waitcnt vmcnt(13)
	ds_write_b128 v186, v[84:87] offset:18432
	global_load_dwordx4 v[76:79], v[176:177], off offset:1280
	v_mfma_f32_32x32x16_bf16 v[4:19], v[168:171], v[172:175], v[4:19]
	ds_read_b128 v[160:163], v194 offset:36960
	ds_read_b128 v[164:167], v195 offset:55392
	s_waitcnt lgkmcnt(6)
	v_mfma_f32_32x32x16_bf16 v[52:67], v[140:143], v[136:139], v[52:67]
	ds_read_b128 v[168:171], v195 offset:60000
	ds_read_b128 v[172:175], v194 offset:41568
	s_waitcnt lgkmcnt(7)
	v_mfma_f32_32x32x16_bf16 v[36:51], v[152:155], v[136:139], v[36:51]
	s_waitcnt vmcnt(13)
	ds_write_b128 v186, v[88:91] offset:23040
	global_load_dwordx4 v[80:83], v[178:179], off offset:1280
	s_waitcnt lgkmcnt(7)
	v_mfma_f32_32x32x16_bf16 v[20:35], v[140:143], v[156:159], v[20:35]
	s_waitcnt vmcnt(13)
	ds_write_b128 v186, v[92:95] offset:27648
	global_load_dwordx4 v[84:87], v[150:151], off offset:1280
	v_mfma_f32_32x32x16_bf16 v[4:19], v[152:155], v[156:159], v[4:19]
	s_waitcnt vmcnt(13)
	ds_write_b128 v186, v[96:99] offset:32256
	global_load_dwordx4 v[88:91], v[180:181], off offset:1280
	s_waitcnt lgkmcnt(5)
	v_mfma_f32_32x32x16_bf16 v[52:67], v[164:167], v[160:163], v[52:67]
	global_load_dwordx4 v[92:95], v[182:183], off offset:1280
	s_waitcnt lgkmcnt(4)
	v_mfma_f32_32x32x16_bf16 v[36:51], v[168:171], v[160:163], v[36:51]
	global_load_dwordx4 v[96:99], v[184:185], off offset:1280
	s_waitcnt lgkmcnt(3)
	v_mfma_f32_32x32x16_bf16 v[20:35], v[164:167], v[172:175], v[20:35]
	v_mfma_f32_32x32x16_bf16 v[4:19], v[168:171], v[172:175], v[4:19]
	s_setprio 0
	s_waitcnt lgkmcnt(0)
	s_barrier
	ds_read_b128 v[136:139], v194
	ds_read_b128 v[140:143], v195 offset:18432
	ds_read_b128 v[152:155], v195 offset:23040
	ds_read_b128 v[156:159], v194 offset:4608
	ds_read_b128 v[160:163], v194 offset:32
	ds_read_b128 v[164:167], v195 offset:18464
	ds_read_b128 v[168:171], v195 offset:23072
	ds_read_b128 v[172:175], v194 offset:4640
	s_setprio 1
	s_waitcnt lgkmcnt(6)
	v_mfma_f32_32x32x16_bf16 v[52:67], v[140:143], v[136:139], v[52:67]
	s_waitcnt vmcnt(15)
	ds_write_b128 v187, v[100:103]
	s_waitcnt lgkmcnt(6)
	v_mfma_f32_32x32x16_bf16 v[36:51], v[152:155], v[136:139], v[36:51]
	s_waitcnt vmcnt(14)
	ds_write_b128 v187, v[104:107] offset:4608
	s_waitcnt lgkmcnt(6)
	v_mfma_f32_32x32x16_bf16 v[20:35], v[140:143], v[156:159], v[20:35]
	s_waitcnt vmcnt(13)
	ds_write_b128 v187, v[108:111] offset:9216
	global_load_dwordx4 v[100:103], v[148:149], off offset:1408
	v_mfma_f32_32x32x16_bf16 v[4:19], v[152:155], v[156:159], v[4:19]
	ds_read_b128 v[136:139], v194 offset:64
	ds_read_b128 v[140:143], v195 offset:18496
	s_waitcnt lgkmcnt(7)
	v_mfma_f32_32x32x16_bf16 v[52:67], v[164:167], v[160:163], v[52:67]
	ds_read_b128 v[152:155], v195 offset:23104
	ds_read_b128 v[156:159], v194 offset:4672
	s_waitcnt lgkmcnt(8)
	v_mfma_f32_32x32x16_bf16 v[36:51], v[168:171], v[160:163], v[36:51]
	s_waitcnt vmcnt(13)
	ds_write_b128 v187, v[112:115] offset:13824
	global_load_dwordx4 v[104:107], v[134:135], off offset:1408
	s_waitcnt lgkmcnt(8)
	v_mfma_f32_32x32x16_bf16 v[20:35], v[164:167], v[172:175], v[20:35]
	s_waitcnt vmcnt(13)
	ds_write_b128 v187, v[116:119] offset:18432
	global_load_dwordx4 v[108:111], v[176:177], off offset:1408
	v_mfma_f32_32x32x16_bf16 v[4:19], v[168:171], v[172:175], v[4:19]
	ds_read_b128 v[160:163], v194 offset:96
	ds_read_b128 v[164:167], v195 offset:18528
	s_waitcnt lgkmcnt(6)
	v_mfma_f32_32x32x16_bf16 v[52:67], v[140:143], v[136:139], v[52:67]
	ds_read_b128 v[168:171], v195 offset:23136
	ds_read_b128 v[172:175], v194 offset:4704
	s_waitcnt lgkmcnt(7)
	v_mfma_f32_32x32x16_bf16 v[36:51], v[152:155], v[136:139], v[36:51]
	s_waitcnt vmcnt(13)
	ds_write_b128 v187, v[120:123] offset:23040
	global_load_dwordx4 v[112:115], v[178:179], off offset:1408
	s_waitcnt lgkmcnt(7)
	v_mfma_f32_32x32x16_bf16 v[20:35], v[140:143], v[156:159], v[20:35]
	s_waitcnt vmcnt(13)
	ds_write_b128 v187, v[124:127] offset:27648
	global_load_dwordx4 v[116:119], v[150:151], off offset:1408
	v_mfma_f32_32x32x16_bf16 v[4:19], v[152:155], v[156:159], v[4:19]
	s_waitcnt vmcnt(13)
	ds_write_b128 v187, v[128:131] offset:32256
	global_load_dwordx4 v[120:123], v[180:181], off offset:1408
	s_waitcnt lgkmcnt(5)
	v_mfma_f32_32x32x16_bf16 v[52:67], v[164:167], v[160:163], v[52:67]
	global_load_dwordx4 v[124:127], v[182:183], off offset:1408
	s_waitcnt lgkmcnt(4)
	v_mfma_f32_32x32x16_bf16 v[36:51], v[168:171], v[160:163], v[36:51]
	global_load_dwordx4 v[128:131], v[184:185], off offset:1408
	s_waitcnt lgkmcnt(3)
	v_mfma_f32_32x32x16_bf16 v[20:35], v[164:167], v[172:175], v[20:35]
	v_mfma_f32_32x32x16_bf16 v[4:19], v[168:171], v[172:175], v[4:19]
	s_setprio 0
	s_waitcnt lgkmcnt(0)
	s_barrier
	ds_read_b128 v[136:139], v194 offset:36864
	ds_read_b128 v[140:143], v195 offset:55296
	ds_read_b128 v[152:155], v195 offset:59904
	ds_read_b128 v[156:159], v194 offset:41472
	ds_read_b128 v[160:163], v194 offset:36896
	ds_read_b128 v[164:167], v195 offset:55328
	ds_read_b128 v[168:171], v195 offset:59936
	ds_read_b128 v[172:175], v194 offset:41504
	s_setprio 1
	s_waitcnt lgkmcnt(6)
	v_mfma_f32_32x32x16_bf16 v[52:67], v[140:143], v[136:139], v[52:67]
	s_waitcnt vmcnt(15)
	ds_write_b128 v186, v[68:71]
	s_waitcnt lgkmcnt(6)
	v_mfma_f32_32x32x16_bf16 v[36:51], v[152:155], v[136:139], v[36:51]
	s_waitcnt vmcnt(14)
	ds_write_b128 v186, v[72:75] offset:4608
	s_waitcnt lgkmcnt(6)
	v_mfma_f32_32x32x16_bf16 v[20:35], v[140:143], v[156:159], v[20:35]
	s_waitcnt vmcnt(13)
	ds_write_b128 v186, v[76:79] offset:9216
	global_load_dwordx4 v[68:71], v[148:149], off offset:1536
	v_mfma_f32_32x32x16_bf16 v[4:19], v[152:155], v[156:159], v[4:19]
	ds_read_b128 v[136:139], v194 offset:36928
	ds_read_b128 v[140:143], v195 offset:55360
	s_waitcnt lgkmcnt(7)
	v_mfma_f32_32x32x16_bf16 v[52:67], v[164:167], v[160:163], v[52:67]
	ds_read_b128 v[152:155], v195 offset:59968
	ds_read_b128 v[156:159], v194 offset:41536
	s_waitcnt lgkmcnt(8)
	v_mfma_f32_32x32x16_bf16 v[36:51], v[168:171], v[160:163], v[36:51]
	s_waitcnt vmcnt(13)
	ds_write_b128 v186, v[80:83] offset:13824
	global_load_dwordx4 v[72:75], v[134:135], off offset:1536
	s_waitcnt lgkmcnt(8)
	v_mfma_f32_32x32x16_bf16 v[20:35], v[164:167], v[172:175], v[20:35]
	s_waitcnt vmcnt(13)
	ds_write_b128 v186, v[84:87] offset:18432
	global_load_dwordx4 v[76:79], v[176:177], off offset:1536
	v_mfma_f32_32x32x16_bf16 v[4:19], v[168:171], v[172:175], v[4:19]
	ds_read_b128 v[160:163], v194 offset:36960
	ds_read_b128 v[164:167], v195 offset:55392
	s_waitcnt lgkmcnt(6)
	v_mfma_f32_32x32x16_bf16 v[52:67], v[140:143], v[136:139], v[52:67]
	ds_read_b128 v[168:171], v195 offset:60000
	ds_read_b128 v[172:175], v194 offset:41568
	s_waitcnt lgkmcnt(7)
	v_mfma_f32_32x32x16_bf16 v[36:51], v[152:155], v[136:139], v[36:51]
	s_waitcnt vmcnt(13)
	ds_write_b128 v186, v[88:91] offset:23040
	global_load_dwordx4 v[80:83], v[178:179], off offset:1536
	s_waitcnt lgkmcnt(7)
	v_mfma_f32_32x32x16_bf16 v[20:35], v[140:143], v[156:159], v[20:35]
	s_waitcnt vmcnt(13)
	ds_write_b128 v186, v[92:95] offset:27648
	global_load_dwordx4 v[84:87], v[150:151], off offset:1536
	v_mfma_f32_32x32x16_bf16 v[4:19], v[152:155], v[156:159], v[4:19]
	s_waitcnt vmcnt(13)
	ds_write_b128 v186, v[96:99] offset:32256
	global_load_dwordx4 v[88:91], v[180:181], off offset:1536
	s_waitcnt lgkmcnt(5)
	v_mfma_f32_32x32x16_bf16 v[52:67], v[164:167], v[160:163], v[52:67]
	global_load_dwordx4 v[92:95], v[182:183], off offset:1536
	s_waitcnt lgkmcnt(4)
	v_mfma_f32_32x32x16_bf16 v[36:51], v[168:171], v[160:163], v[36:51]
	global_load_dwordx4 v[96:99], v[184:185], off offset:1536
	s_waitcnt lgkmcnt(3)
	v_mfma_f32_32x32x16_bf16 v[20:35], v[164:167], v[172:175], v[20:35]
	v_mfma_f32_32x32x16_bf16 v[4:19], v[168:171], v[172:175], v[4:19]
	s_setprio 0
	s_waitcnt lgkmcnt(0)
	s_barrier
	ds_read_b128 v[136:139], v194
	ds_read_b128 v[140:143], v195 offset:18432
	ds_read_b128 v[152:155], v195 offset:23040
	ds_read_b128 v[156:159], v194 offset:4608
	ds_read_b128 v[160:163], v194 offset:32
	ds_read_b128 v[164:167], v195 offset:18464
	ds_read_b128 v[168:171], v195 offset:23072
	ds_read_b128 v[172:175], v194 offset:4640
	s_setprio 1
	s_waitcnt lgkmcnt(6)
	v_mfma_f32_32x32x16_bf16 v[52:67], v[140:143], v[136:139], v[52:67]
	s_waitcnt vmcnt(15)
	ds_write_b128 v187, v[100:103]
	s_waitcnt lgkmcnt(6)
	v_mfma_f32_32x32x16_bf16 v[36:51], v[152:155], v[136:139], v[36:51]
	s_waitcnt vmcnt(14)
	ds_write_b128 v187, v[104:107] offset:4608
	s_waitcnt lgkmcnt(6)
	v_mfma_f32_32x32x16_bf16 v[20:35], v[140:143], v[156:159], v[20:35]
	s_waitcnt vmcnt(13)
	ds_write_b128 v187, v[108:111] offset:9216
	global_load_dwordx4 v[100:103], v[148:149], off offset:1664
	v_mfma_f32_32x32x16_bf16 v[4:19], v[152:155], v[156:159], v[4:19]
	ds_read_b128 v[136:139], v194 offset:64
	ds_read_b128 v[140:143], v195 offset:18496
	s_waitcnt lgkmcnt(7)
	v_mfma_f32_32x32x16_bf16 v[52:67], v[164:167], v[160:163], v[52:67]
	ds_read_b128 v[152:155], v195 offset:23104
	ds_read_b128 v[156:159], v194 offset:4672
	s_waitcnt lgkmcnt(8)
	v_mfma_f32_32x32x16_bf16 v[36:51], v[168:171], v[160:163], v[36:51]
	s_waitcnt vmcnt(13)
	ds_write_b128 v187, v[112:115] offset:13824
	global_load_dwordx4 v[104:107], v[134:135], off offset:1664
	s_waitcnt lgkmcnt(8)
	v_mfma_f32_32x32x16_bf16 v[20:35], v[164:167], v[172:175], v[20:35]
	s_waitcnt vmcnt(13)
	ds_write_b128 v187, v[116:119] offset:18432
	global_load_dwordx4 v[108:111], v[176:177], off offset:1664
	v_mfma_f32_32x32x16_bf16 v[4:19], v[168:171], v[172:175], v[4:19]
	ds_read_b128 v[160:163], v194 offset:96
	ds_read_b128 v[164:167], v195 offset:18528
	s_waitcnt lgkmcnt(6)
	v_mfma_f32_32x32x16_bf16 v[52:67], v[140:143], v[136:139], v[52:67]
	ds_read_b128 v[168:171], v195 offset:23136
	ds_read_b128 v[172:175], v194 offset:4704
	s_waitcnt lgkmcnt(7)
	v_mfma_f32_32x32x16_bf16 v[36:51], v[152:155], v[136:139], v[36:51]
	s_waitcnt vmcnt(13)
	ds_write_b128 v187, v[120:123] offset:23040
	global_load_dwordx4 v[112:115], v[178:179], off offset:1664
	s_waitcnt lgkmcnt(7)
	v_mfma_f32_32x32x16_bf16 v[20:35], v[140:143], v[156:159], v[20:35]
	s_waitcnt vmcnt(13)
	ds_write_b128 v187, v[124:127] offset:27648
	global_load_dwordx4 v[116:119], v[150:151], off offset:1664
	v_mfma_f32_32x32x16_bf16 v[4:19], v[152:155], v[156:159], v[4:19]
	s_waitcnt vmcnt(13)
	ds_write_b128 v187, v[128:131] offset:32256
	global_load_dwordx4 v[120:123], v[180:181], off offset:1664
	s_waitcnt lgkmcnt(5)
	v_mfma_f32_32x32x16_bf16 v[52:67], v[164:167], v[160:163], v[52:67]
	global_load_dwordx4 v[124:127], v[182:183], off offset:1664
	s_waitcnt lgkmcnt(4)
	v_mfma_f32_32x32x16_bf16 v[36:51], v[168:171], v[160:163], v[36:51]
	global_load_dwordx4 v[128:131], v[184:185], off offset:1664
	s_waitcnt lgkmcnt(3)
	v_mfma_f32_32x32x16_bf16 v[20:35], v[164:167], v[172:175], v[20:35]
	v_mfma_f32_32x32x16_bf16 v[4:19], v[168:171], v[172:175], v[4:19]
	s_setprio 0
	s_waitcnt lgkmcnt(0)
	s_barrier
	ds_read_b128 v[136:139], v194 offset:36864
	ds_read_b128 v[140:143], v195 offset:55296
	ds_read_b128 v[152:155], v195 offset:59904
	ds_read_b128 v[156:159], v194 offset:41472
	ds_read_b128 v[160:163], v194 offset:36896
	ds_read_b128 v[164:167], v195 offset:55328
	ds_read_b128 v[168:171], v195 offset:59936
	ds_read_b128 v[172:175], v194 offset:41504
	s_setprio 1
	s_waitcnt lgkmcnt(6)
	v_mfma_f32_32x32x16_bf16 v[52:67], v[140:143], v[136:139], v[52:67]
	s_waitcnt vmcnt(15)
	ds_write_b128 v186, v[68:71]
	s_waitcnt lgkmcnt(6)
	v_mfma_f32_32x32x16_bf16 v[36:51], v[152:155], v[136:139], v[36:51]
	s_waitcnt vmcnt(14)
	ds_write_b128 v186, v[72:75] offset:4608
	s_waitcnt lgkmcnt(6)
	v_mfma_f32_32x32x16_bf16 v[20:35], v[140:143], v[156:159], v[20:35]
	s_waitcnt vmcnt(13)
	ds_write_b128 v186, v[76:79] offset:9216
	global_load_dwordx4 v[68:71], v[148:149], off offset:1792
	v_mfma_f32_32x32x16_bf16 v[4:19], v[152:155], v[156:159], v[4:19]
	ds_read_b128 v[136:139], v194 offset:36928
	ds_read_b128 v[140:143], v195 offset:55360
	s_waitcnt lgkmcnt(7)
	v_mfma_f32_32x32x16_bf16 v[52:67], v[164:167], v[160:163], v[52:67]
	ds_read_b128 v[152:155], v195 offset:59968
	ds_read_b128 v[156:159], v194 offset:41536
	s_waitcnt lgkmcnt(8)
	v_mfma_f32_32x32x16_bf16 v[36:51], v[168:171], v[160:163], v[36:51]
	s_waitcnt vmcnt(13)
	ds_write_b128 v186, v[80:83] offset:13824
	global_load_dwordx4 v[72:75], v[134:135], off offset:1792
	s_waitcnt lgkmcnt(8)
	v_mfma_f32_32x32x16_bf16 v[20:35], v[164:167], v[172:175], v[20:35]
	s_waitcnt vmcnt(13)
	ds_write_b128 v186, v[84:87] offset:18432
	global_load_dwordx4 v[76:79], v[176:177], off offset:1792
	v_mfma_f32_32x32x16_bf16 v[4:19], v[168:171], v[172:175], v[4:19]
	ds_read_b128 v[160:163], v194 offset:36960
	ds_read_b128 v[164:167], v195 offset:55392
	s_waitcnt lgkmcnt(6)
	v_mfma_f32_32x32x16_bf16 v[52:67], v[140:143], v[136:139], v[52:67]
	ds_read_b128 v[168:171], v195 offset:60000
	ds_read_b128 v[172:175], v194 offset:41568
	s_waitcnt lgkmcnt(7)
	v_mfma_f32_32x32x16_bf16 v[36:51], v[152:155], v[136:139], v[36:51]
	s_waitcnt vmcnt(13)
	ds_write_b128 v186, v[88:91] offset:23040
	global_load_dwordx4 v[80:83], v[178:179], off offset:1792
	s_waitcnt lgkmcnt(7)
	v_mfma_f32_32x32x16_bf16 v[20:35], v[140:143], v[156:159], v[20:35]
	s_waitcnt vmcnt(13)
	ds_write_b128 v186, v[92:95] offset:27648
	global_load_dwordx4 v[84:87], v[150:151], off offset:1792
	v_mfma_f32_32x32x16_bf16 v[4:19], v[152:155], v[156:159], v[4:19]
	s_waitcnt vmcnt(13)
	ds_write_b128 v186, v[96:99] offset:32256
	global_load_dwordx4 v[88:91], v[180:181], off offset:1792
	s_waitcnt lgkmcnt(5)
	v_mfma_f32_32x32x16_bf16 v[52:67], v[164:167], v[160:163], v[52:67]
	global_load_dwordx4 v[92:95], v[182:183], off offset:1792
	s_waitcnt lgkmcnt(4)
	v_mfma_f32_32x32x16_bf16 v[36:51], v[168:171], v[160:163], v[36:51]
	global_load_dwordx4 v[96:99], v[184:185], off offset:1792
	s_waitcnt lgkmcnt(3)
	v_mfma_f32_32x32x16_bf16 v[20:35], v[164:167], v[172:175], v[20:35]
	v_mfma_f32_32x32x16_bf16 v[4:19], v[168:171], v[172:175], v[4:19]
	s_setprio 0
	s_waitcnt lgkmcnt(0)
	s_barrier
	ds_read_b128 v[136:139], v194
	ds_read_b128 v[140:143], v195 offset:18432
	ds_read_b128 v[152:155], v195 offset:23040
	ds_read_b128 v[156:159], v194 offset:4608
	ds_read_b128 v[160:163], v194 offset:32
	ds_read_b128 v[164:167], v195 offset:18464
	ds_read_b128 v[168:171], v195 offset:23072
	ds_read_b128 v[172:175], v194 offset:4640
	s_setprio 1
	s_waitcnt lgkmcnt(6)
	v_mfma_f32_32x32x16_bf16 v[52:67], v[140:143], v[136:139], v[52:67]
	s_waitcnt vmcnt(15)
	ds_write_b128 v187, v[100:103]
	s_waitcnt lgkmcnt(6)
	v_mfma_f32_32x32x16_bf16 v[36:51], v[152:155], v[136:139], v[36:51]
	s_waitcnt vmcnt(14)
	ds_write_b128 v187, v[104:107] offset:4608
	s_waitcnt lgkmcnt(6)
	v_mfma_f32_32x32x16_bf16 v[20:35], v[140:143], v[156:159], v[20:35]
	s_waitcnt vmcnt(13)
	ds_write_b128 v187, v[108:111] offset:9216
	global_load_dwordx4 v[100:103], v[148:149], off offset:1920
	v_mfma_f32_32x32x16_bf16 v[4:19], v[152:155], v[156:159], v[4:19]
	ds_read_b128 v[136:139], v194 offset:64
	ds_read_b128 v[140:143], v195 offset:18496
	s_waitcnt lgkmcnt(7)
	v_mfma_f32_32x32x16_bf16 v[52:67], v[164:167], v[160:163], v[52:67]
	ds_read_b128 v[152:155], v195 offset:23104
	ds_read_b128 v[156:159], v194 offset:4672
	s_waitcnt lgkmcnt(8)
	v_mfma_f32_32x32x16_bf16 v[36:51], v[168:171], v[160:163], v[36:51]
	s_waitcnt vmcnt(13)
	ds_write_b128 v187, v[112:115] offset:13824
	global_load_dwordx4 v[104:107], v[134:135], off offset:1920
	s_waitcnt lgkmcnt(8)
	v_mfma_f32_32x32x16_bf16 v[20:35], v[164:167], v[172:175], v[20:35]
	s_waitcnt vmcnt(13)
	ds_write_b128 v187, v[116:119] offset:18432
	global_load_dwordx4 v[108:111], v[176:177], off offset:1920
	v_mfma_f32_32x32x16_bf16 v[4:19], v[168:171], v[172:175], v[4:19]
	ds_read_b128 v[160:163], v194 offset:96
	ds_read_b128 v[164:167], v195 offset:18528
	s_waitcnt lgkmcnt(6)
	v_mfma_f32_32x32x16_bf16 v[52:67], v[140:143], v[136:139], v[52:67]
	ds_read_b128 v[168:171], v195 offset:23136
	ds_read_b128 v[172:175], v194 offset:4704
	s_waitcnt lgkmcnt(7)
	v_mfma_f32_32x32x16_bf16 v[36:51], v[152:155], v[136:139], v[36:51]
	s_waitcnt vmcnt(13)
	ds_write_b128 v187, v[120:123] offset:23040
	global_load_dwordx4 v[112:115], v[178:179], off offset:1920
	s_waitcnt lgkmcnt(7)
	v_mfma_f32_32x32x16_bf16 v[20:35], v[140:143], v[156:159], v[20:35]
	s_waitcnt vmcnt(13)
	ds_write_b128 v187, v[124:127] offset:27648
	global_load_dwordx4 v[116:119], v[150:151], off offset:1920
	v_mfma_f32_32x32x16_bf16 v[4:19], v[152:155], v[156:159], v[4:19]
	s_waitcnt vmcnt(13)
	ds_write_b128 v187, v[128:131] offset:32256
	global_load_dwordx4 v[120:123], v[180:181], off offset:1920
	s_waitcnt lgkmcnt(5)
	v_mfma_f32_32x32x16_bf16 v[52:67], v[164:167], v[160:163], v[52:67]
	global_load_dwordx4 v[124:127], v[182:183], off offset:1920
	s_waitcnt lgkmcnt(4)
	v_mfma_f32_32x32x16_bf16 v[36:51], v[168:171], v[160:163], v[36:51]
	global_load_dwordx4 v[128:131], v[184:185], off offset:1920
	s_waitcnt lgkmcnt(3)
	v_mfma_f32_32x32x16_bf16 v[20:35], v[164:167], v[172:175], v[20:35]
	v_mfma_f32_32x32x16_bf16 v[4:19], v[168:171], v[172:175], v[4:19]
	s_setprio 0
	s_waitcnt lgkmcnt(0)
	s_barrier
	ds_read_b128 v[136:139], v194 offset:36864
	ds_read_b128 v[140:143], v195 offset:55296
	ds_read_b128 v[152:155], v195 offset:59904
	ds_read_b128 v[156:159], v194 offset:41472
	ds_read_b128 v[160:163], v194 offset:36896
	ds_read_b128 v[164:167], v195 offset:55328
	ds_read_b128 v[168:171], v195 offset:59936
	ds_read_b128 v[172:175], v194 offset:41504
	s_setprio 1
	s_waitcnt lgkmcnt(6)
	v_mfma_f32_32x32x16_bf16 v[52:67], v[140:143], v[136:139], v[52:67]
	s_waitcnt vmcnt(15)
	ds_write_b128 v186, v[68:71]
	s_waitcnt lgkmcnt(6)
	v_mfma_f32_32x32x16_bf16 v[36:51], v[152:155], v[136:139], v[36:51]
	s_waitcnt vmcnt(14)
	ds_write_b128 v186, v[72:75] offset:4608
	s_waitcnt lgkmcnt(6)
	v_mfma_f32_32x32x16_bf16 v[20:35], v[140:143], v[156:159], v[20:35]
	s_waitcnt vmcnt(13)
	ds_write_b128 v186, v[76:79] offset:9216
	v_mfma_f32_32x32x16_bf16 v[4:19], v[152:155], v[156:159], v[4:19]
	ds_read_b128 v[136:139], v194 offset:36928
	ds_read_b128 v[140:143], v195 offset:55360
	s_waitcnt lgkmcnt(7)
	v_mfma_f32_32x32x16_bf16 v[52:67], v[164:167], v[160:163], v[52:67]
	ds_read_b128 v[152:155], v195 offset:59968
	ds_read_b128 v[156:159], v194 offset:41536
	s_waitcnt lgkmcnt(8)
	v_mfma_f32_32x32x16_bf16 v[36:51], v[168:171], v[160:163], v[36:51]
	s_waitcnt vmcnt(12)
	ds_write_b128 v186, v[80:83] offset:13824
	s_waitcnt lgkmcnt(8)
	v_mfma_f32_32x32x16_bf16 v[20:35], v[164:167], v[172:175], v[20:35]
	s_waitcnt vmcnt(11)
	ds_write_b128 v186, v[84:87] offset:18432
	v_mfma_f32_32x32x16_bf16 v[4:19], v[168:171], v[172:175], v[4:19]
	ds_read_b128 v[160:163], v194 offset:36960
	ds_read_b128 v[164:167], v195 offset:55392
	s_waitcnt lgkmcnt(6)
	v_mfma_f32_32x32x16_bf16 v[52:67], v[140:143], v[136:139], v[52:67]
	ds_read_b128 v[168:171], v195 offset:60000
	ds_read_b128 v[172:175], v194 offset:41568
	s_waitcnt lgkmcnt(7)
	v_mfma_f32_32x32x16_bf16 v[36:51], v[152:155], v[136:139], v[36:51]
	s_waitcnt vmcnt(10)
	ds_write_b128 v186, v[88:91] offset:23040
	s_waitcnt lgkmcnt(7)
	v_mfma_f32_32x32x16_bf16 v[20:35], v[140:143], v[156:159], v[20:35]
	s_waitcnt vmcnt(9)
	ds_write_b128 v186, v[92:95] offset:27648
	v_mfma_f32_32x32x16_bf16 v[4:19], v[152:155], v[156:159], v[4:19]
	s_waitcnt vmcnt(8)
	ds_write_b128 v186, v[96:99] offset:32256
	s_waitcnt lgkmcnt(5)
	v_mfma_f32_32x32x16_bf16 v[52:67], v[164:167], v[160:163], v[52:67]
	s_waitcnt lgkmcnt(4)
	v_mfma_f32_32x32x16_bf16 v[36:51], v[168:171], v[160:163], v[36:51]
	s_waitcnt lgkmcnt(3)
	v_mfma_f32_32x32x16_bf16 v[20:35], v[164:167], v[172:175], v[20:35]
	v_mfma_f32_32x32x16_bf16 v[4:19], v[168:171], v[172:175], v[4:19]
	s_setprio 0
	s_waitcnt lgkmcnt(0)
	s_barrier
	ds_read_b128 v[136:139], v194
	ds_read_b128 v[140:143], v195 offset:18432
	ds_read_b128 v[152:155], v195 offset:23040
	ds_read_b128 v[156:159], v194 offset:4608
	ds_read_b128 v[160:163], v194 offset:32
	ds_read_b128 v[164:167], v195 offset:18464
	ds_read_b128 v[168:171], v195 offset:23072
	ds_read_b128 v[172:175], v194 offset:4640
	s_setprio 1
	s_waitcnt lgkmcnt(6)
	v_mfma_f32_32x32x16_bf16 v[52:67], v[140:143], v[136:139], v[52:67]
	s_waitcnt vmcnt(7)
	ds_write_b128 v187, v[100:103]
	s_waitcnt lgkmcnt(6)
	v_mfma_f32_32x32x16_bf16 v[36:51], v[152:155], v[136:139], v[36:51]
	s_waitcnt vmcnt(6)
	ds_write_b128 v187, v[104:107] offset:4608
	s_waitcnt lgkmcnt(6)
	v_mfma_f32_32x32x16_bf16 v[20:35], v[140:143], v[156:159], v[20:35]
	s_waitcnt vmcnt(5)
	ds_write_b128 v187, v[108:111] offset:9216
	v_mfma_f32_32x32x16_bf16 v[4:19], v[152:155], v[156:159], v[4:19]
	ds_read_b128 v[136:139], v194 offset:64
	ds_read_b128 v[140:143], v195 offset:18496
	s_waitcnt lgkmcnt(7)
	v_mfma_f32_32x32x16_bf16 v[52:67], v[164:167], v[160:163], v[52:67]
	ds_read_b128 v[152:155], v195 offset:23104
	ds_read_b128 v[156:159], v194 offset:4672
	s_waitcnt lgkmcnt(8)
	v_mfma_f32_32x32x16_bf16 v[36:51], v[168:171], v[160:163], v[36:51]
	s_waitcnt vmcnt(4)
	ds_write_b128 v187, v[112:115] offset:13824
	s_waitcnt lgkmcnt(8)
	v_mfma_f32_32x32x16_bf16 v[20:35], v[164:167], v[172:175], v[20:35]
	s_waitcnt vmcnt(3)
	ds_write_b128 v187, v[116:119] offset:18432
	v_mfma_f32_32x32x16_bf16 v[4:19], v[168:171], v[172:175], v[4:19]
	ds_read_b128 v[160:163], v194 offset:96
	ds_read_b128 v[164:167], v195 offset:18528
	s_waitcnt lgkmcnt(6)
	v_mfma_f32_32x32x16_bf16 v[52:67], v[140:143], v[136:139], v[52:67]
	ds_read_b128 v[168:171], v195 offset:23136
	ds_read_b128 v[172:175], v194 offset:4704
	s_waitcnt lgkmcnt(7)
	v_mfma_f32_32x32x16_bf16 v[36:51], v[152:155], v[136:139], v[36:51]
	s_waitcnt vmcnt(2)
	ds_write_b128 v187, v[120:123] offset:23040
	s_waitcnt lgkmcnt(7)
	v_mfma_f32_32x32x16_bf16 v[20:35], v[140:143], v[156:159], v[20:35]
	s_waitcnt vmcnt(1)
	ds_write_b128 v187, v[124:127] offset:27648
	v_mfma_f32_32x32x16_bf16 v[4:19], v[152:155], v[156:159], v[4:19]
	s_waitcnt vmcnt(0)
	ds_write_b128 v187, v[128:131] offset:32256
	s_waitcnt lgkmcnt(5)
	v_mfma_f32_32x32x16_bf16 v[52:67], v[164:167], v[160:163], v[52:67]
	s_waitcnt lgkmcnt(4)
	v_mfma_f32_32x32x16_bf16 v[36:51], v[168:171], v[160:163], v[36:51]
	s_waitcnt lgkmcnt(3)
	v_mfma_f32_32x32x16_bf16 v[20:35], v[164:167], v[172:175], v[20:35]
	v_mfma_f32_32x32x16_bf16 v[4:19], v[168:171], v[172:175], v[4:19]
	s_setprio 0
	s_waitcnt lgkmcnt(0)
	s_barrier
	ds_read_b128 v[136:139], v194 offset:36864
	ds_read_b128 v[140:143], v195 offset:55296
	ds_read_b128 v[152:155], v195 offset:59904
	ds_read_b128 v[156:159], v194 offset:41472
	ds_read_b128 v[160:163], v194 offset:36896
	ds_read_b128 v[164:167], v195 offset:55328
	ds_read_b128 v[168:171], v195 offset:59936
	ds_read_b128 v[172:175], v194 offset:41504
	s_setprio 1
	s_waitcnt lgkmcnt(6)
	v_mfma_f32_32x32x16_bf16 v[52:67], v[140:143], v[136:139], v[52:67]
	s_waitcnt lgkmcnt(5)
	v_mfma_f32_32x32x16_bf16 v[36:51], v[152:155], v[136:139], v[36:51]
	s_waitcnt lgkmcnt(4)
	v_mfma_f32_32x32x16_bf16 v[20:35], v[140:143], v[156:159], v[20:35]
	v_mfma_f32_32x32x16_bf16 v[4:19], v[152:155], v[156:159], v[4:19]
	ds_read_b128 v[136:139], v194 offset:36928
	ds_read_b128 v[140:143], v195 offset:55360
	s_waitcnt lgkmcnt(4)
	v_mfma_f32_32x32x16_bf16 v[52:67], v[164:167], v[160:163], v[52:67]
	ds_read_b128 v[152:155], v195 offset:59968
	ds_read_b128 v[156:159], v194 offset:41536
	s_waitcnt lgkmcnt(5)
	v_mfma_f32_32x32x16_bf16 v[36:51], v[168:171], v[160:163], v[36:51]
	s_waitcnt lgkmcnt(4)
	v_mfma_f32_32x32x16_bf16 v[20:35], v[164:167], v[172:175], v[20:35]
	v_mfma_f32_32x32x16_bf16 v[4:19], v[168:171], v[172:175], v[4:19]
	ds_read_b128 v[160:163], v194 offset:36960
	ds_read_b128 v[164:167], v195 offset:55392
	s_waitcnt lgkmcnt(4)
	v_mfma_f32_32x32x16_bf16 v[52:67], v[140:143], v[136:139], v[52:67]
	ds_read_b128 v[168:171], v195 offset:60000
	ds_read_b128 v[172:175], v194 offset:41568
	s_waitcnt lgkmcnt(5)
	v_mfma_f32_32x32x16_bf16 v[36:51], v[152:155], v[136:139], v[36:51]
	s_waitcnt lgkmcnt(4)
	v_mfma_f32_32x32x16_bf16 v[20:35], v[140:143], v[156:159], v[20:35]
	v_mfma_f32_32x32x16_bf16 v[4:19], v[152:155], v[156:159], v[4:19]
	s_waitcnt lgkmcnt(2)
	v_mfma_f32_32x32x16_bf16 v[52:67], v[164:167], v[160:163], v[52:67]
	s_waitcnt lgkmcnt(1)
	v_mfma_f32_32x32x16_bf16 v[36:51], v[168:171], v[160:163], v[36:51]
	s_waitcnt lgkmcnt(0)
	v_mfma_f32_32x32x16_bf16 v[20:35], v[164:167], v[172:175], v[20:35]
	v_mfma_f32_32x32x16_bf16 v[4:19], v[168:171], v[172:175], v[4:19]
	s_setprio 0
	s_nop 7
	s_nop 4
	v_mov_b32_e32 v188, 0x12010
	s_add_i32 s2, s76, s70
	s_and_b32 s0, s2, 0xfffffe00
	s_cmpk_eq_i32 s0, 0xc00
	s_cselect_b64 s[0:1], -1, 0
	s_and_b64 s[0:1], s[26:27], s[0:1]
	s_cmpk_lt_i32 s2, 0xd00
	s_movk_i32 s3, 0xff00
	s_cselect_b32 s3, 0x100, s3
	s_and_b64 s[0:1], s[0:1], exec
	s_cselect_b32 s0, s3, 0
	s_add_i32 s0, s0, s2
	s_cmpk_lt_i32 s2, 0xe10
	s_cselect_b32 s0, s0, 0xd00
	s_cmpk_gt_i32 s0, 0xcff
	v_mov_b64_e32 v[146:147], v[150:151]
	v_mov_b64_e32 v[144:145], v[148:149]
	s_barrier
	s_cbranch_scc1 .LBB0_303
	s_lshl_b32 s1, s0, 18
	v_readlane_b32 s12, v252, 47
	v_mov_b32_e32 v2, v0
	s_and_b32 s1, s1, 0xfc0000
	v_readlane_b32 s18, v252, 53
	v_readlane_b32 s19, v252, 54
	v_ashrrev_i32_e32 v68, 3, v2
	s_add_u32 s2, s18, s1
	v_ashrrev_i32_e32 v69, 31, v68
	s_addc_u32 s3, s19, 0
	v_lshlrev_b64 v[68:69], 11, v[68:69]
	v_lshlrev_b32_e32 v2, 4, v2
	v_lshl_add_u64 v[70:71], s[2:3], 0, v[68:69]
	v_and_b32_e32 v2, 0x70, v2
	s_ashr_i32 s0, s0, 6
	v_lshl_add_u64 v[144:145], v[70:71], 0, v[2:3]
	s_ashr_i32 s1, s0, 31
	v_add_co_u32_e32 v76, vcc, s33, v144
	s_lshl_b64 s[0:1], s[0:1], 18
	s_nop 0
	v_addc_co_u32_e32 v77, vcc, 0, v145, vcc
	s_add_u32 s0, s68, s0
	v_add_co_u32_e32 v80, vcc, s78, v144
	s_addc_u32 s1, s69, s1
	s_nop 0
	v_addc_co_u32_e32 v81, vcc, 0, v145, vcc
	v_lshl_add_u64 v[68:69], s[0:1], 0, v[68:69]
	v_add_co_u32_e32 v84, vcc, s79, v144
	v_lshl_add_u64 v[146:147], v[68:69], 0, v[2:3]
	s_nop 0
	v_addc_co_u32_e32 v85, vcc, 0, v145, vcc
	v_add_co_u32_e32 v92, vcc, s33, v146
	v_readlane_b32 s13, v252, 48
	s_nop 0
	v_addc_co_u32_e32 v93, vcc, 0, v147, vcc
	v_add_co_u32_e32 v96, vcc, s78, v146
	v_readlane_b32 s14, v252, 49
	s_nop 0
	v_addc_co_u32_e32 v97, vcc, 0, v147, vcc
	v_add_co_u32_e32 v128, vcc, 0x30000, v146
	v_readlane_b32 s15, v252, 50
	s_nop 0
	v_addc_co_u32_e32 v129, vcc, 0, v147, vcc
	global_load_dwordx4 v[68:71], v[144:145], off
	global_load_dwordx4 v[100:103], v[144:145], off offset:128
	global_load_dwordx4 v[72:75], v[76:77], off
	global_load_dwordx4 v[104:107], v[76:77], off offset:128
	s_nop 0
	global_load_dwordx4 v[76:79], v[80:81], off
	global_load_dwordx4 v[108:111], v[80:81], off offset:128
	s_nop 0
	global_load_dwordx4 v[80:83], v[84:85], off
	global_load_dwordx4 v[112:115], v[84:85], off offset:128
	s_nop 0
	global_load_dwordx4 v[84:87], v[146:147], off
	global_load_dwordx4 v[116:119], v[146:147], off offset:128
	global_load_dwordx4 v[88:91], v[92:93], off
	global_load_dwordx4 v[120:123], v[92:93], off offset:128
	s_nop 0
	global_load_dwordx4 v[92:95], v[96:97], off
	global_load_dwordx4 v[124:127], v[96:97], off offset:128
	s_nop 0
	global_load_dwordx4 v[96:99], v[128:129], off
	s_nop 0
	global_load_dwordx4 v[128:131], v[128:129], off offset:128
	v_readlane_b32 s16, v252, 51
	v_readlane_b32 s17, v252, 52
